# attention: softmax row sums moved from 32 VALU adds per tile to 4 bf16 MFMAs (ones x P) accumulating in f32
# speedup vs baseline: 1.0302x; 1.0046x over previous
; #define LAS __attribute__((address_space(3)))
; template <bool MLA>
; DI void attn_phase(const int TID, const int BID, LAS unsigned char* lds, const Params& p, bool need_ctx) {
;     constexpr int DK = MLA ? 96 : 64;
;     constexpr int NKS = DK / 16;
;     constexpr int KSTR = (DK + 8) * 2;
;     constexpr int VSTR = 192;
;     constexpr int KBUF = 64 * KSTR, VBUF = 64 * VSTR;
;     constexpr int NKV = MLA ? 16 : 4;
;     constexpr int QS = 16 * DK;
;     const float sc = (MLA ? 0.10206207261596575f : 0.125f) * 1.4426950408889634f;
;     const int tid = TID, wid = tid >> 6, lane = tid & 63, r = lane & 31, hh = lane >> 5;
;     const int n_items = 1024 + (need_ctx ? 128 : 0);
;     bf16_t* O = P_WSB(OFF_H);
;     for (int item = BID; item < n_items; item += gridDim.x) {
;         int b, head, row0, nk;
;         if (item < 1024) {
;             const int rnd = item >> 8, w = item & 255, xcd = w & 7, slot = w >> 3, qb = slot & 7;
;             if (MLA) { const int grp = (rnd * 8 + xcd) * 4 + (slot >> 3); b = grp >> 4; head = grp & 15; }
;             else { const int grp = rnd * 8 + xcd; b = grp >> 2; head = (grp & 3) * 4 + (slot >> 3); }
;             row0 = b * 2048 + qb * 256; nk = NKEY;
;         }
;         else { const int it = item - 1024; b = it >> 4; head = it & 15; row0 = TL + b * 256; nk = 256; }
;         const int kvh = MLA ? head : (head >> 2);
;         const bf16_t* Kb = P_WSB(OFF_K) + (size_t)(b * NKV + kvh) * NKEY * 64;
;         const bf16_t* Vb = P_WSB(OFF_VT) + (size_t)(b * NKV + kvh) * NKEY * 64;
;         const bf16_t* Pb = P_WSB(OFF_KPE) + (size_t)b * NKEY * 32;
;         bf16x8 qf[NKS];
;         {
;             const bf16_t* qp = P_WSB(OFF_Q) + (size_t)(row0 + wid * 32 + r) * QS + head * DK + hh * 8;
; #pragma unroll
;             for (int ks = 0; ks < NKS; ++ks) qf[ks] = *(const bf16x8*)(qp + ks * 16);
;         }
;         u32x4 kreg, vreg; u32x2 preg = {0u, 0u};
.LBB0_293:
	s_andn2_b64 vcc, exec, s[0:1]
	s_cbranch_vccnz .LBB0_773
	s_add_i32 s0, s23, 0x22040
	v_writelane_b32 v255, s0, 32
	s_nop 0
	v_readlane_b32 s0, v255, 21
	s_cmp_lt_i32 s0, 2
	s_mov_b64 s[0:1], -1
	s_cbranch_scc1 .LBB0_501
	v_readlane_b32 s0, v255, 21
	s_cmp_gt_i32 s0, 2
	v_readlane_b32 s0, v255, 24
	v_readlane_b32 s1, v255, 25
	s_mov_b64 s[2:3], -1
	s_nop 0
	v_cndmask_b32_e64 v0, 0, 1, s[0:1]
	v_cmp_ne_u32_e64 s[0:1], 1, v0
	s_cbranch_scc0 .LBB0_340
	v_readlane_b32 s2, v255, 27
	s_cmp_lt_i32 s2, 3
	s_movk_i32 s2, 0x480
	s_cselect_b32 s8, s2, 0x400
	v_readlane_b32 s3, v255, 28
	s_cmp_lt_i32 s83, s8
	s_cselect_b64 s[2:3], -1, 0
	v_cndmask_b32_e64 v0, 0, 1, s[2:3]
	s_mov_b64 s[4:5], -1
	s_and_b64 vcc, exec, s[0:1]
	v_cmp_ne_u32_e64 s[2:3], 1, v0
	s_cbranch_vccnz .LBB0_318
	s_and_b64 vcc, exec, s[2:3]
	s_cbranch_vccnz .LBB0_317
	v_and_b32_e32 v208, 31, v174
	v_bfe_u32 v209, v174, 5, 1
	v_lshrrev_b32_e32 v210, 6, v174
	v_lshrrev_b32_e32 v211, 3, v174
	v_and_b32_e32 v212, 7, v174
	v_mov_b32_e32 v213, s23
	s_movk_i32 s15, 0xd0
	v_mad_u32_u24 v243, v208, s15, v213
	v_lshl_add_u32 v243, v209, 4, v243
	v_mad_u32_u24 v218, v211, s15, v213
	v_lshl_add_u32 v219, v212, 3, v218
	v_add_u32_e32 v219, 0x80, v219
	v_lshl_add_u32 v218, v212, 4, v218
	s_movk_i32 s15, 0xc0
	v_bfe_u32 v214, v174, 2, 2
	v_lshl_add_u32 v214, v209, 2, v214
	v_mad_u32_u24 v220, v214, s15, v213
	v_bfe_u32 v215, v174, 4, 1
	v_and_b32_e32 v216, 3, v174
	v_lshlrev_b32_e32 v215, 5, v215
	v_lshl_add_u32 v215, v216, 3, v215
	v_add_u32_e32 v220, v220, v215
	v_add_u32_e32 v220, 0x6800, v220
	v_mad_u32_u24 v221, v211, s15, v213
	v_lshl_add_u32 v221, v212, 4, v221
	v_add_u32_e32 v221, 0x6800, v221
	v_lshlrev_b32_e32 v225, 7, v211
	v_lshl_add_u32 v225, v212, 4, v225
	v_lshlrev_b32_e32 v165, 6, v211
	v_lshl_add_u32 v165, v212, 3, v165
	v_lshl_add_u32 v217, v210, 5, v208
	s_movk_i32 s15, 0xc00
	v_mul_u32_u24_e32 v171, s15, v217
	v_lshl_add_u32 v171, v209, 4, v171
	v_lshlrev_b32_e32 v172, 11, v217
	v_lshl_add_u32 v172, v209, 4, v172
	v_mov_b32_e32 v167, 0
	v_mov_b32_e32 v246, 0x3f803f80
	v_mov_b32_e32 v247, 0x3f803f80
	v_mov_b32_e32 v248, 0x3f803f80
	v_mov_b32_e32 v249, 0x3f803f80
	v_readfirstlane_b32 s58, v210
	s_mov_b32 s6, s83
	s_lshr_b32 s58, s58, 2

; #define AT_GLOADK(k0) do { kreg = *(const u32x4*)(Kb + (size_t)((k0) + (tid >> 3)) * 64 + (tid & 7) * 8); \
;             if (MLA) preg = *(const u32x2*)(Pb + (size_t)((k0) + (tid >> 3)) * 32 + (tid & 7) * 4); } while (0)
; #define AT_GLOADV(k0) do { vreg = *(const u32x4*)(Vb + (size_t)((k0) + (tid >> 3)) * 64 + (tid & 7) * 8); } while (0)
; #define AT_WRITEK(buf) do { *(LAS u32x4*)(lds + (buf) * KBUF + (tid >> 3) * KSTR + (tid & 7) * 16) = kreg; \
;             if (MLA) *(LAS u32x2*)(lds + (buf) * KBUF + (tid >> 3) * KSTR + 128 + (tid & 7) * 8) = preg; } while (0)
; #define AT_WRITEV(buf) do { *(LAS u32x4*)(lds + 2 * KBUF + (buf) * VBUF + (tid >> 3) * VSTR + (tid & 7) * 16) = vreg; } while (0)
; template <bool MLA>
; DI void attn_phase(const int TID, const int BID, LAS unsigned char* lds, const Params& p, bool need_ctx) {
;     ...
;         const bf16_t* Kb = P_WSB(OFF_K) + (size_t)(b * NKV + kvh) * NKEY * 64;
;         const bf16_t* Vb = P_WSB(OFF_VT) + (size_t)(b * NKV + kvh) * NKEY * 64;
;         const bf16_t* Pb = P_WSB(OFF_KPE) + (size_t)b * NKEY * 32;
;         bf16x8 qf[NKS];
;         {
;             const bf16_t* qp = P_WSB(OFF_Q) + (size_t)(row0 + wid * 32 + r) * QS + head * DK + hh * 8;
; #pragma unroll
;             for (int ks = 0; ks < NKS; ++ks) qf[ks] = *(const bf16x8*)(qp + ks * 16);
;         }
;         u32x4 kreg, vreg; u32x2 preg = {0u, 0u};
;     ...
;         f32x16 o0, o1, sa0, sa1, sb0, sb1;
; #pragma unroll
;         for (int j = 0; j < 16; ++j) { o0[j] = 0.f; o1[j] = 0.f; }
;         float mrun = -1e30f, lsum = 0.f;
;         if (wid >= 4) __builtin_amdgcn_s_setprio(1);
;         const int ntile = nk >> 6;
;         AT_GLOADK(0); AT_GLOADV(0); AT_WRITEK(0); AT_WRITEV(0);
;         AT_GLOADK(64); AT_WRITEK(1);
;         __syncthreads();
;         AT_QK(sa0, sa1, 0);
;         __syncthreads();
.Lamla_decoded:
	s_mov_b32 s19, s18
	s_lshl_b32 s21, s15, 4
	s_add_i32 s21, s21, s19
	s_mul_i32 s21, s21, 0x48000
	s_add_u32 s2, s26, s21
	s_addc_u32 s3, s27, 0
	v_readlane_b32 s60, v254, 36
	v_readlane_b32 s61, v254, 37
	s_add_u32 s4, s60, s21
	s_addc_u32 s5, s61, 0
	v_readlane_b32 s60, v254, 38
	v_readlane_b32 s61, v254, 39
	s_mul_i32 s21, s15, 0x24000
	s_add_u32 s10, s60, s21
	s_addc_u32 s11, s61, 0
	v_readlane_b32 s60, v254, 27
	v_readlane_b32 s61, v254, 28
	s_mul_i32 s21, s20, 0xc00
	s_mul_i32 s55, s18, 0xc0
	s_add_i32 s21, s21, s55
	s_add_u32 s12, s60, s21
	s_addc_u32 s13, s61, 0
	v_readlane_b32 s60, v254, 34
	v_readlane_b32 s61, v254, 35
	s_lshl_b32 s21, s20, 11
	s_lshl_b32 s55, s18, 7
	s_add_i32 s21, s21, s55
	s_add_u32 s16, s60, s21
	s_addc_u32 s17, s61, 0
	global_load_dwordx4 v[112:115], v171, s[12:13]
	global_load_dwordx4 v[116:119], v171, s[12:13] offset:32
	global_load_dwordx4 v[120:123], v171, s[12:13] offset:64
	global_load_dwordx4 v[124:127], v171, s[12:13] offset:96
	global_load_dwordx4 v[128:131], v171, s[12:13] offset:128
	global_load_dwordx4 v[132:135], v171, s[12:13] offset:160
	global_load_dwordx4 v[136:139], v225, s[2:3]
	global_load_dwordx2 v[208:209], v165, s[10:11]
	s_add_u32 s2, s2, 0x2000
	s_addc_u32 s3, s3, 0
	s_add_u32 s10, s10, 0x1000
	s_addc_u32 s11, s11, 0
	global_load_dwordx4 v[140:143], v225, s[2:3]
	global_load_dwordx2 v[210:211], v165, s[10:11]
	s_add_u32 s2, s2, 0x2000
	s_addc_u32 s3, s3, 0
	s_add_u32 s10, s10, 0x1000
	s_addc_u32 s11, s11, 0
	global_load_dwordx4 v[144:147], v225, s[4:5]
	s_add_u32 s4, s4, 0x2000
	s_addc_u32 s5, s5, 0
	global_load_dwordx4 v[152:155], v225, s[2:3]
	global_load_dwordx2 v[160:161], v165, s[10:11]
	s_add_u32 s2, s2, 0x2000
	s_addc_u32 s3, s3, 0
	s_add_u32 s10, s10, 0x1000
	s_addc_u32 s11, s11, 0
	global_load_dwordx4 v[156:159], v225, s[4:5]
	s_add_u32 s4, s4, 0x2000
	s_addc_u32 s5, s5, 0
	s_mov_b32 s52, 0x3000
	s_mov_b32 s53, 0x6000
	s_mov_b32 s54, 0
	v_mov_b64_e32 v[0:1], 0
	v_mov_b64_e32 v[2:3], 0
	v_mov_b64_e32 v[4:5], 0
	v_mov_b64_e32 v[6:7], 0
	v_mov_b64_e32 v[8:9], 0
	v_mov_b64_e32 v[10:11], 0
	v_mov_b64_e32 v[12:13], 0
	v_mov_b64_e32 v[14:15], 0
	v_mov_b64_e32 v[16:17], 0
	v_mov_b64_e32 v[18:19], 0
	v_mov_b64_e32 v[20:21], 0
	v_mov_b64_e32 v[22:23], 0
	v_mov_b64_e32 v[24:25], 0
	v_mov_b64_e32 v[26:27], 0
	v_mov_b64_e32 v[28:29], 0
	v_mov_b64_e32 v[30:31], 0
	v_mov_b32_e32 v162, 0xf149f2ca
	v_mov_b32_e32 v164, 0xf149f2ca
	v_mov_b32_e32 v163, 0x7149f2ca
	v_mov_b64_e32 v[226:227], 0
	v_mov_b64_e32 v[228:229], 0
	v_mov_b64_e32 v[230:231], 0
	v_mov_b64_e32 v[232:233], 0
	v_mov_b64_e32 v[234:235], 0
	v_mov_b64_e32 v[236:237], 0
	v_mov_b64_e32 v[238:239], 0
	v_mov_b64_e32 v[240:241], 0
	s_barrier
	s_waitcnt vmcnt(7)
	ds_write_b128 v218, v[136:139]
	s_waitcnt vmcnt(6)
	ds_write_b64 v219, v[208:209]
	s_waitcnt vmcnt(5)
	ds_write_b128 v218, v[140:143] offset:13312
	s_waitcnt vmcnt(4)
	ds_write_b64 v219, v[210:211] offset:13312
	s_waitcnt vmcnt(3)
	ds_write_b128 v221, v[144:147]
	s_waitcnt lgkmcnt(0)
	s_barrier
	s_cmp_eq_u32 s58, 0
	s_cbranch_scc1 .Lamla_prio
	s_setprio 1
.Lamla_prio:
	ds_read_b128 v[136:139], v243 offset:0
	ds_read_b128 v[140:143], v243 offset:6656
	ds_read_b128 v[144:147], v243 offset:32
	ds_read_b128 v[148:151], v243 offset:6688
	s_waitcnt lgkmcnt(3)
	v_mfma_f32_32x32x16_bf16 v[32:47], v[136:139], v[112:115], 0
	ds_read_b128 v[136:139], v243 offset:64
	s_waitcnt lgkmcnt(3)
	v_mfma_f32_32x32x16_bf16 v[48:63], v[140:143], v[112:115], 0
	ds_read_b128 v[140:143], v243 offset:6720
	s_waitcnt lgkmcnt(3)
	v_mfma_f32_32x32x16_bf16 v[32:47], v[144:147], v[116:119], v[32:47]
	ds_read_b128 v[144:147], v243 offset:96
	s_waitcnt lgkmcnt(3)
	v_mfma_f32_32x32x16_bf16 v[48:63], v[148:151], v[116:119], v[48:63]
	ds_read_b128 v[148:151], v243 offset:6752
	s_waitcnt lgkmcnt(3)
	v_mfma_f32_32x32x16_bf16 v[32:47], v[136:139], v[120:123], v[32:47]
	ds_read_b128 v[136:139], v243 offset:128
	s_waitcnt lgkmcnt(3)
	v_mfma_f32_32x32x16_bf16 v[48:63], v[140:143], v[120:123], v[48:63]
	ds_read_b128 v[140:143], v243 offset:6784
	s_waitcnt lgkmcnt(3)
	v_mfma_f32_32x32x16_bf16 v[32:47], v[144:147], v[124:127], v[32:47]
	ds_read_b128 v[144:147], v243 offset:160
	s_waitcnt lgkmcnt(3)
	v_mfma_f32_32x32x16_bf16 v[48:63], v[148:151], v[124:127], v[48:63]
	ds_read_b128 v[148:151], v243 offset:6816
	s_waitcnt lgkmcnt(3)
	v_mfma_f32_32x32x16_bf16 v[32:47], v[136:139], v[128:131], v[32:47]
	s_waitcnt lgkmcnt(2)
	v_mfma_f32_32x32x16_bf16 v[48:63], v[140:143], v[128:131], v[48:63]
	s_waitcnt lgkmcnt(1)
	v_mfma_f32_32x32x16_bf16 v[32:47], v[144:147], v[132:135], v[32:47]
	s_waitcnt lgkmcnt(0)
	v_mfma_f32_32x32x16_bf16 v[48:63], v[148:151], v[132:135], v[48:63]
	s_waitcnt lgkmcnt(0)
	s_nop 7
	s_barrier
	ds_read_b128 v[136:139], v243 offset:13312
	ds_read_b128 v[140:143], v243 offset:19968
	ds_read_b128 v[144:147], v243 offset:13344
	ds_read_b128 v[148:151], v243 offset:20000
	s_waitcnt lgkmcnt(3)
	v_mfma_f32_32x32x16_bf16 v[64:79], v[136:139], v[112:115], 0
	v_max3_f32 v168, v32, v33, v34
	v_max3_f32 v170, v48, v49, v50
	v_max3_f32 v168, v168, v35, v36
	v_max3_f32 v170, v170, v51, v52
	v_max3_f32 v168, v168, v37, v38
	v_max3_f32 v170, v170, v53, v54
	v_max3_f32 v168, v168, v39, v40
	v_max3_f32 v170, v170, v55, v56
	v_max3_f32 v168, v168, v41, v42
	v_max3_f32 v170, v170, v57, v58
	v_max3_f32 v168, v168, v43, v44
	v_max3_f32 v170, v170, v59, v60
	ds_read_b128 v[136:139], v243 offset:13376
	s_mov_b32 s55, s52
	s_mov_b32 s52, s53
	s_mov_b32 s53, s54
	s_mov_b32 s54, s55
	s_mov_b32 s9, 0
	s_waitcnt lgkmcnt(3)
	v_mfma_f32_32x32x16_bf16 v[80:95], v[140:143], v[112:115], 0
	v_max3_f32 v168, v168, v45, v46
	v_max3_f32 v170, v170, v61, v62
	v_max_f32_e32 v168, v168, v47
	v_max_f32_e32 v170, v170, v63
	v_max_f32_e32 v168, v168, v170
	v_mov_b32_e32 v170, v168
	s_nop 1
	v_permlane32_swap_b32_e32 v168, v170
	v_max_f32_e32 v168, v168, v170
	v_mul_f32_e32 v168, 0x3e16c740, v168
	v_cmp_gt_f32_e32 vcc, v168, v164
	s_cbranch_vccz .Lamla_nors_1
	v_max_f32_e32 v170, v162, v168
	v_sub_f32_e32 v166, v162, v170
	v_exp_f32_e32 v166, v166
	v_mov_b32_e32 v162, v170
	v_add_f32_e32 v164, 0x41000000, v170
	v_xor_b32_e32 v163, 0x80000000, v170
	s_mov_b32 s9, 1
.Lamla_nors_1:
	ds_read_b128 v[140:143], v243 offset:20032
	global_load_dwordx4 v[208:211], v225, s[2:3]
	global_load_dwordx2 v[216:217], v165, s[10:11]
	global_load_dwordx4 v[212:215], v225, s[4:5]
	s_add_u32 s2, s2, 0x2000
	s_addc_u32 s3, s3, 0
	s_add_u32 s10, s10, 0x1000
	s_addc_u32 s11, s11, 0
	s_add_u32 s4, s4, 0x2000
	s_addc_u32 s5, s5, 0
	v_add_u32_e32 v223, s53, v220
	v_add_u32_e32 v224, s54, v221
	s_waitcnt lgkmcnt(3)
	v_mfma_f32_32x32x16_bf16 v[64:79], v[144:147], v[116:119], v[64:79]
	v_fmamk_f32 v32, v32, 0x3e16c740, v163
	v_fmamk_f32 v48, v48, 0x3e16c740, v163
	v_exp_f32_e32 v32, v32
	v_exp_f32_e32 v48, v48
	v_fmamk_f32 v33, v33, 0x3e16c740, v163
	v_fmamk_f32 v49, v49, 0x3e16c740, v163
	v_exp_f32_e32 v33, v33
	v_exp_f32_e32 v49, v49
	ds_read_b128 v[144:147], v243 offset:13408
	s_waitcnt lgkmcnt(3)
	v_mfma_f32_32x32x16_bf16 v[80:95], v[148:151], v[116:119], v[80:95]
	v_fmamk_f32 v34, v34, 0x3e16c740, v163
	v_fmamk_f32 v50, v50, 0x3e16c740, v163
	v_exp_f32_e32 v34, v34
	v_exp_f32_e32 v50, v50
	v_cvt_pk_bf16_f32 v96, v32, v33
	v_cvt_pk_bf16_f32 v104, v48, v49
	v_fmamk_f32 v35, v35, 0x3e16c740, v163
	v_fmamk_f32 v51, v51, 0x3e16c740, v163
	ds_read_b128 v[148:151], v243 offset:20064
	s_waitcnt lgkmcnt(3)
	v_mfma_f32_32x32x16_bf16 v[64:79], v[136:139], v[120:123], v[64:79]
	v_exp_f32_e32 v35, v35
	v_exp_f32_e32 v51, v51
	v_fmamk_f32 v36, v36, 0x3e16c740, v163
	v_fmamk_f32 v52, v52, 0x3e16c740, v163
	v_exp_f32_e32 v36, v36
	v_exp_f32_e32 v52, v52
	v_cvt_pk_bf16_f32 v97, v34, v35
	v_cvt_pk_bf16_f32 v105, v50, v51
	ds_read_b128 v[136:139], v243 offset:13440
	s_waitcnt lgkmcnt(3)
	v_mfma_f32_32x32x16_bf16 v[80:95], v[140:143], v[120:123], v[80:95]
	v_fmamk_f32 v37, v37, 0x3e16c740, v163
	v_fmamk_f32 v53, v53, 0x3e16c740, v163
	v_exp_f32_e32 v37, v37
	v_exp_f32_e32 v53, v53
	v_fmamk_f32 v38, v38, 0x3e16c740, v163
	v_fmamk_f32 v54, v54, 0x3e16c740, v163
	v_exp_f32_e32 v38, v38
	v_exp_f32_e32 v54, v54
	ds_read_b128 v[140:143], v243 offset:20096
	s_waitcnt lgkmcnt(3)
	v_mfma_f32_32x32x16_bf16 v[64:79], v[144:147], v[124:127], v[64:79]
	v_cvt_pk_bf16_f32 v98, v36, v37
	v_cvt_pk_bf16_f32 v106, v52, v53
	v_fmamk_f32 v39, v39, 0x3e16c740, v163
	v_fmamk_f32 v55, v55, 0x3e16c740, v163
	v_exp_f32_e32 v39, v39
	v_exp_f32_e32 v55, v55
	v_fmamk_f32 v40, v40, 0x3e16c740, v163
	v_fmamk_f32 v56, v56, 0x3e16c740, v163
	ds_read_b128 v[144:147], v243 offset:13472
	ds_read_b64_tr_b16 v[176:177], v223 offset:0
	ds_read_b64_tr_b16 v[178:179], v223 offset:1536
	s_waitcnt vmcnt(5)
	ds_write_b128 v218, v[152:155]
	s_waitcnt vmcnt(4)
	ds_write_b64 v219, v[160:161]
	s_waitcnt vmcnt(3)
	ds_write_b128 v224, v[156:159]
	s_waitcnt lgkmcnt(8)
	v_mfma_f32_32x32x16_bf16 v[80:95], v[148:151], v[124:127], v[80:95]
	v_exp_f32_e32 v40, v40
	v_exp_f32_e32 v56, v56
	v_cvt_pk_bf16_f32 v99, v38, v39
	v_cvt_pk_bf16_f32 v107, v54, v55
	v_fmamk_f32 v41, v41, 0x3e16c740, v163
	v_fmamk_f32 v57, v57, 0x3e16c740, v163
	v_exp_f32_e32 v41, v41
	v_exp_f32_e32 v57, v57
	ds_read_b128 v[148:151], v243 offset:20128
	ds_read_b64_tr_b16 v[180:181], v223 offset:64
	ds_read_b64_tr_b16 v[182:183], v223 offset:1600
	s_waitcnt lgkmcnt(10)
	v_mfma_f32_32x32x16_bf16 v[64:79], v[136:139], v[128:131], v[64:79]
	v_fmamk_f32 v42, v42, 0x3e16c740, v163
	v_fmamk_f32 v58, v58, 0x3e16c740, v163
	v_exp_f32_e32 v42, v42
	v_exp_f32_e32 v58, v58
	v_cvt_pk_bf16_f32 v100, v40, v41
	v_cvt_pk_bf16_f32 v108, v56, v57
	v_fmamk_f32 v43, v43, 0x3e16c740, v163
	v_fmamk_f32 v59, v59, 0x3e16c740, v163
	v_exp_f32_e32 v43, v43
	ds_read_b64_tr_b16 v[184:185], v223 offset:6144
	ds_read_b64_tr_b16 v[186:187], v223 offset:7680
	s_waitcnt lgkmcnt(11)
	v_mfma_f32_32x32x16_bf16 v[80:95], v[140:143], v[128:131], v[80:95]
	v_exp_f32_e32 v59, v59
	v_fmamk_f32 v44, v44, 0x3e16c740, v163
	v_fmamk_f32 v60, v60, 0x3e16c740, v163
	v_exp_f32_e32 v44, v44
	v_exp_f32_e32 v60, v60
	v_cvt_pk_bf16_f32 v101, v42, v43
	v_cvt_pk_bf16_f32 v109, v58, v59
	ds_read_b64_tr_b16 v[188:189], v223 offset:6208
	ds_read_b64_tr_b16 v[190:191], v223 offset:7744
	s_waitcnt lgkmcnt(12)
	v_mfma_f32_32x32x16_bf16 v[64:79], v[144:147], v[132:135], v[64:79]
	v_fmamk_f32 v45, v45, 0x3e16c740, v163
	v_fmamk_f32 v61, v61, 0x3e16c740, v163
	v_exp_f32_e32 v45, v45
	v_exp_f32_e32 v61, v61
	v_fmamk_f32 v46, v46, 0x3e16c740, v163
	v_fmamk_f32 v62, v62, 0x3e16c740, v163
	v_exp_f32_e32 v46, v46
	v_exp_f32_e32 v62, v62
	s_waitcnt lgkmcnt(6)
	v_mfma_f32_32x32x16_bf16 v[80:95], v[148:151], v[132:135], v[80:95]
	v_cvt_pk_bf16_f32 v102, v44, v45
	v_cvt_pk_bf16_f32 v110, v60, v61
	v_fmamk_f32 v47, v47, 0x3e16c740, v163
	v_fmamk_f32 v63, v63, 0x3e16c740, v163
	v_exp_f32_e32 v47, v47
	v_exp_f32_e32 v63, v63
	v_cvt_pk_bf16_f32 v103, v46, v47
	v_cvt_pk_bf16_f32 v111, v62, v63
	s_waitcnt lgkmcnt(0)
	s_barrier
	s_cmp_eq_u32 s7, 0
	s_cbranch_scc1 .Lamla_tail
.Lamla_loop:
	ds_read_b128 v[136:139], v243 offset:0
	ds_read_b128 v[140:143], v243 offset:6656
	ds_read_b128 v[144:147], v243 offset:32
	ds_read_b128 v[148:151], v243 offset:6688
	v_mfma_f32_32x32x16_bf16 v[0:15], v[176:179], v[96:99], v[0:15]
	v_max3_f32 v168, v64, v65, v66
	v_max3_f32 v170, v80, v81, v82
	v_max3_f32 v168, v168, v67, v68
	v_max3_f32 v170, v170, v83, v84
	v_max3_f32 v168, v168, v69, v70
	v_max3_f32 v170, v170, v85, v86
	s_mov_b32 s55, s52
	s_mov_b32 s52, s53
	s_mov_b32 s53, s54
	s_mov_b32 s54, s55
	s_mov_b32 s9, 0
	v_mfma_f32_32x32x16_bf16 v[16:31], v[180:183], v[96:99], v[16:31]
	v_max3_f32 v168, v168, v71, v72
	v_max3_f32 v170, v170, v87, v88
	v_max3_f32 v168, v168, v73, v74
	v_max3_f32 v170, v170, v89, v90
	v_max3_f32 v168, v168, v75, v76
	v_max3_f32 v170, v170, v91, v92
	global_load_dwordx4 v[152:155], v225, s[2:3]
	global_load_dwordx2 v[160:161], v165, s[10:11]
	global_load_dwordx4 v[156:159], v225, s[4:5]
	s_add_u32 s2, s2, 0x2000
	s_addc_u32 s3, s3, 0
	s_add_u32 s10, s10, 0x1000
	s_addc_u32 s11, s11, 0
	s_add_u32 s4, s4, 0x2000
	s_addc_u32 s5, s5, 0
	v_add_u32_e32 v222, s53, v220
	v_add_u32_e32 v224, s54, v221
	v_mfma_f32_32x32x16_bf16 v[226:241], v[246:249], v[96:99], v[226:241]
	v_max3_f32 v168, v168, v77, v78
	v_max3_f32 v170, v170, v93, v94
	v_max_f32_e32 v168, v168, v79
	v_max_f32_e32 v170, v170, v95
	v_max_f32_e32 v168, v168, v170
	v_mfma_f32_32x32x16_bf16 v[0:15], v[184:187], v[104:107], v[0:15]
	v_mov_b32_e32 v170, v168
	s_nop 1
	v_permlane32_swap_b32_e32 v168, v170
	v_max_f32_e32 v168, v168, v170
	v_mul_f32_e32 v168, 0x3e16c740, v168
	v_cmp_gt_f32_e32 vcc, v168, v164
	s_cbranch_vccz .Lamla_nors_2
	v_max_f32_e32 v170, v162, v168
	v_sub_f32_e32 v166, v162, v170
	v_exp_f32_e32 v166, v166
	v_mov_b32_e32 v162, v170
	v_add_f32_e32 v164, 0x41000000, v170
	v_xor_b32_e32 v163, 0x80000000, v170
	s_mov_b32 s9, 1
.Lamla_nors_2:
	ds_read_b64_tr_b16 v[192:193], v223 offset:3072
	ds_read_b64_tr_b16 v[194:195], v223 offset:4608
	v_mfma_f32_32x32x16_bf16 v[16:31], v[188:191], v[104:107], v[16:31]
	v_fmamk_f32 v64, v64, 0x3e16c740, v163
	v_fmamk_f32 v80, v80, 0x3e16c740, v163
	v_exp_f32_e32 v64, v64
	v_exp_f32_e32 v80, v80
	ds_read_b64_tr_b16 v[196:197], v223 offset:3136
	ds_read_b64_tr_b16 v[198:199], v223 offset:4672
	v_mfma_f32_32x32x16_bf16 v[226:241], v[246:249], v[104:107], v[226:241]
	v_fmamk_f32 v65, v65, 0x3e16c740, v163
	v_fmamk_f32 v81, v81, 0x3e16c740, v163
	v_exp_f32_e32 v65, v65
	v_exp_f32_e32 v81, v81
	ds_read_b64_tr_b16 v[200:201], v223 offset:9216
	ds_read_b64_tr_b16 v[202:203], v223 offset:10752
	s_waitcnt lgkmcnt(9)
	v_mfma_f32_32x32x16_bf16 v[32:47], v[136:139], v[112:115], 0
	v_fmamk_f32 v66, v66, 0x3e16c740, v163
	v_fmamk_f32 v82, v82, 0x3e16c740, v163
	v_exp_f32_e32 v66, v66
	v_exp_f32_e32 v82, v82
	ds_read_b128 v[136:139], v243 offset:64
	ds_read_b64_tr_b16 v[204:205], v223 offset:9280
	ds_read_b64_tr_b16 v[206:207], v223 offset:10816
	s_waitcnt lgkmcnt(11)
	v_mfma_f32_32x32x16_bf16 v[48:63], v[140:143], v[112:115], 0
	v_cvt_pk_bf16_f32 v96, v64, v65
	v_cvt_pk_bf16_f32 v104, v80, v81
	v_fmamk_f32 v67, v67, 0x3e16c740, v163
	v_fmamk_f32 v83, v83, 0x3e16c740, v163
	ds_read_b128 v[140:143], v243 offset:6720
	s_waitcnt lgkmcnt(11)
	v_mfma_f32_32x32x16_bf16 v[32:47], v[144:147], v[116:119], v[32:47]
	v_exp_f32_e32 v67, v67
	v_exp_f32_e32 v83, v83
	v_fmamk_f32 v68, v68, 0x3e16c740, v163
	v_fmamk_f32 v84, v84, 0x3e16c740, v163
	ds_read_b128 v[144:147], v243 offset:96
	s_waitcnt lgkmcnt(11)
	v_mfma_f32_32x32x16_bf16 v[48:63], v[148:151], v[116:119], v[48:63]
	v_exp_f32_e32 v68, v68
	v_exp_f32_e32 v84, v84
	v_cvt_pk_bf16_f32 v97, v66, v67
	v_cvt_pk_bf16_f32 v105, v82, v83
	ds_read_b128 v[148:151], v243 offset:6752
	s_waitcnt lgkmcnt(5)
	v_mfma_f32_32x32x16_bf16 v[32:47], v[136:139], v[120:123], v[32:47]
	v_fmamk_f32 v69, v69, 0x3e16c740, v163
	v_fmamk_f32 v85, v85, 0x3e16c740, v163
	v_exp_f32_e32 v69, v69
	v_exp_f32_e32 v85, v85
	ds_read_b128 v[136:139], v243 offset:128
	s_waitcnt lgkmcnt(3)
	v_mfma_f32_32x32x16_bf16 v[48:63], v[140:143], v[120:123], v[48:63]
	v_fmamk_f32 v70, v70, 0x3e16c740, v163
	v_fmamk_f32 v86, v86, 0x3e16c740, v163
	v_exp_f32_e32 v70, v70
	v_exp_f32_e32 v86, v86
	ds_read_b128 v[140:143], v243 offset:6784
	s_waitcnt lgkmcnt(3)
	v_mfma_f32_32x32x16_bf16 v[32:47], v[144:147], v[124:127], v[32:47]
	v_cvt_pk_bf16_f32 v98, v68, v69
	v_cvt_pk_bf16_f32 v106, v84, v85
	v_fmamk_f32 v71, v71, 0x3e16c740, v163
	v_fmamk_f32 v87, v87, 0x3e16c740, v163
	v_exp_f32_e32 v71, v71
	ds_read_b128 v[144:147], v243 offset:160
	s_waitcnt lgkmcnt(3)
	v_mfma_f32_32x32x16_bf16 v[48:63], v[148:151], v[124:127], v[48:63]
	v_exp_f32_e32 v87, v87
	v_fmamk_f32 v72, v72, 0x3e16c740, v163
	v_fmamk_f32 v88, v88, 0x3e16c740, v163
	ds_read_b128 v[148:151], v243 offset:6816
	s_waitcnt lgkmcnt(3)
	v_mfma_f32_32x32x16_bf16 v[32:47], v[136:139], v[128:131], v[32:47]
	v_exp_f32_e32 v72, v72
	v_exp_f32_e32 v88, v88
	v_cvt_pk_bf16_f32 v99, v70, v71
	v_cvt_pk_bf16_f32 v107, v86, v87
	s_waitcnt vmcnt(5)
	ds_write_b128 v218, v[208:211] offset:13312
	s_waitcnt vmcnt(4)
	ds_write_b64 v219, v[216:217] offset:13312
	s_waitcnt vmcnt(3)
	ds_write_b128 v224, v[212:215]
	s_waitcnt lgkmcnt(5)
	v_mfma_f32_32x32x16_bf16 v[48:63], v[140:143], v[128:131], v[48:63]
	v_fmamk_f32 v73, v73, 0x3e16c740, v163
	v_fmamk_f32 v89, v89, 0x3e16c740, v163
	v_exp_f32_e32 v73, v73
	v_exp_f32_e32 v89, v89
	s_waitcnt lgkmcnt(4)
	v_mfma_f32_32x32x16_bf16 v[32:47], v[144:147], v[132:135], v[32:47]
	v_fmamk_f32 v74, v74, 0x3e16c740, v163
	v_fmamk_f32 v90, v90, 0x3e16c740, v163
	v_exp_f32_e32 v74, v74
	v_exp_f32_e32 v90, v90
	s_waitcnt lgkmcnt(3)
	v_mfma_f32_32x32x16_bf16 v[48:63], v[148:151], v[132:135], v[48:63]
	v_fmamk_f32 v75, v75, 0x3e16c740, v163
	v_fmamk_f32 v91, v91, 0x3e16c740, v163
	v_exp_f32_e32 v75, v75
	v_exp_f32_e32 v91, v91
	v_mfma_f32_32x32x16_bf16 v[0:15], v[192:195], v[100:103], v[0:15]
	v_fmamk_f32 v76, v76, 0x3e16c740, v163
	v_fmamk_f32 v92, v92, 0x3e16c740, v163
	v_exp_f32_e32 v76, v76
	ds_read_b64_tr_b16 v[176:177], v222 offset:0
	ds_read_b64_tr_b16 v[178:179], v222 offset:1536
	v_mfma_f32_32x32x16_bf16 v[16:31], v[196:199], v[100:103], v[16:31]
	v_exp_f32_e32 v92, v92
	v_fmamk_f32 v77, v77, 0x3e16c740, v163
	v_fmamk_f32 v93, v93, 0x3e16c740, v163
	v_exp_f32_e32 v77, v77
	ds_read_b64_tr_b16 v[180:181], v222 offset:64
	ds_read_b64_tr_b16 v[182:183], v222 offset:1600
	v_mfma_f32_32x32x16_bf16 v[226:241], v[246:249], v[100:103], v[226:241]
	v_cvt_pk_bf16_f32 v100, v72, v73
	v_cvt_pk_bf16_f32 v101, v74, v75
	v_exp_f32_e32 v93, v93
	v_fmamk_f32 v78, v78, 0x3e16c740, v163
	v_fmamk_f32 v94, v94, 0x3e16c740, v163
	v_exp_f32_e32 v78, v78
	ds_read_b64_tr_b16 v[184:185], v222 offset:6144
	ds_read_b64_tr_b16 v[186:187], v222 offset:7680
	v_mfma_f32_32x32x16_bf16 v[0:15], v[200:203], v[108:111], v[0:15]
	v_exp_f32_e32 v94, v94
	v_cvt_pk_bf16_f32 v102, v76, v77
	v_fmamk_f32 v79, v79, 0x3e16c740, v163
	v_fmamk_f32 v95, v95, 0x3e16c740, v163
	ds_read_b64_tr_b16 v[188:189], v222 offset:6208
	ds_read_b64_tr_b16 v[190:191], v222 offset:7744
	v_mfma_f32_32x32x16_bf16 v[16:31], v[204:207], v[108:111], v[16:31]
	v_exp_f32_e32 v79, v79
	v_exp_f32_e32 v95, v95
	v_cvt_pk_bf16_f32 v103, v78, v79
	v_mfma_f32_32x32x16_bf16 v[226:241], v[246:249], v[108:111], v[226:241]
	v_cvt_pk_bf16_f32 v108, v88, v89
	v_cvt_pk_bf16_f32 v109, v90, v91
	v_cvt_pk_bf16_f32 v110, v92, v93
	v_cvt_pk_bf16_f32 v111, v94, v95
	s_cmp_lg_u32 s9, 0
	s_cbranch_scc0 .Lamla_noresc_3
	s_nop 15
	v_pk_mul_f32 v[0:1], v[0:1], v[166:167] op_sel_hi:[1,0]
	v_pk_mul_f32 v[2:3], v[2:3], v[166:167] op_sel_hi:[1,0]
	v_pk_mul_f32 v[4:5], v[4:5], v[166:167] op_sel_hi:[1,0]
	v_pk_mul_f32 v[6:7], v[6:7], v[166:167] op_sel_hi:[1,0]
	v_pk_mul_f32 v[8:9], v[8:9], v[166:167] op_sel_hi:[1,0]
	v_pk_mul_f32 v[10:11], v[10:11], v[166:167] op_sel_hi:[1,0]
	v_pk_mul_f32 v[12:13], v[12:13], v[166:167] op_sel_hi:[1,0]
	v_pk_mul_f32 v[14:15], v[14:15], v[166:167] op_sel_hi:[1,0]
	v_pk_mul_f32 v[16:17], v[16:17], v[166:167] op_sel_hi:[1,0]
	v_pk_mul_f32 v[18:19], v[18:19], v[166:167] op_sel_hi:[1,0]
	v_pk_mul_f32 v[20:21], v[20:21], v[166:167] op_sel_hi:[1,0]
	v_pk_mul_f32 v[22:23], v[22:23], v[166:167] op_sel_hi:[1,0]
	v_pk_mul_f32 v[24:25], v[24:25], v[166:167] op_sel_hi:[1,0]
	v_pk_mul_f32 v[26:27], v[26:27], v[166:167] op_sel_hi:[1,0]
	v_pk_mul_f32 v[28:29], v[28:29], v[166:167] op_sel_hi:[1,0]
	v_pk_mul_f32 v[30:31], v[30:31], v[166:167] op_sel_hi:[1,0]
	v_mul_f32_e32 v226, v226, v166
.Lamla_noresc_3:
	s_waitcnt lgkmcnt(0)
	s_barrier
	ds_read_b128 v[136:139], v243 offset:13312
	ds_read_b128 v[140:143], v243 offset:19968
	ds_read_b128 v[144:147], v243 offset:13344
	ds_read_b128 v[148:151], v243 offset:20000
	v_mfma_f32_32x32x16_bf16 v[0:15], v[176:179], v[96:99], v[0:15]
	v_max3_f32 v168, v32, v33, v34
	v_max3_f32 v170, v48, v49, v50
	v_max3_f32 v168, v168, v35, v36
	v_max3_f32 v170, v170, v51, v52
	v_max3_f32 v168, v168, v37, v38
	v_max3_f32 v170, v170, v53, v54
	s_mov_b32 s55, s52
	s_mov_b32 s52, s53
	s_mov_b32 s53, s54
	s_mov_b32 s54, s55
	s_mov_b32 s9, 0
	v_mfma_f32_32x32x16_bf16 v[16:31], v[180:183], v[96:99], v[16:31]
	v_max3_f32 v168, v168, v39, v40
	v_max3_f32 v170, v170, v55, v56
	v_max3_f32 v168, v168, v41, v42
	v_max3_f32 v170, v170, v57, v58
	v_max3_f32 v168, v168, v43, v44
	v_max3_f32 v170, v170, v59, v60
	global_load_dwordx4 v[208:211], v225, s[2:3]
	global_load_dwordx2 v[216:217], v165, s[10:11]
	global_load_dwordx4 v[212:215], v225, s[4:5]
	s_add_u32 s2, s2, 0x2000
	s_addc_u32 s3, s3, 0
	s_add_u32 s10, s10, 0x1000
	s_addc_u32 s11, s11, 0
	s_add_u32 s4, s4, 0x2000
	s_addc_u32 s5, s5, 0
	v_add_u32_e32 v223, s53, v220
	v_add_u32_e32 v224, s54, v221
	v_mfma_f32_32x32x16_bf16 v[226:241], v[246:249], v[96:99], v[226:241]
	v_max3_f32 v168, v168, v45, v46
	v_max3_f32 v170, v170, v61, v62
	v_max_f32_e32 v168, v168, v47
	v_max_f32_e32 v170, v170, v63
	v_max_f32_e32 v168, v168, v170
	v_mfma_f32_32x32x16_bf16 v[0:15], v[184:187], v[104:107], v[0:15]
	v_mov_b32_e32 v170, v168
	s_nop 1
	v_permlane32_swap_b32_e32 v168, v170
	v_max_f32_e32 v168, v168, v170
	v_mul_f32_e32 v168, 0x3e16c740, v168
	v_cmp_gt_f32_e32 vcc, v168, v164
	s_cbranch_vccz .Lamla_nors_4
	v_max_f32_e32 v170, v162, v168
	v_sub_f32_e32 v166, v162, v170
	v_exp_f32_e32 v166, v166
	v_mov_b32_e32 v162, v170
	v_add_f32_e32 v164, 0x41000000, v170
	v_xor_b32_e32 v163, 0x80000000, v170
	s_mov_b32 s9, 1
.Lamla_nors_4:
	ds_read_b64_tr_b16 v[192:193], v222 offset:3072
	ds_read_b64_tr_b16 v[194:195], v222 offset:4608
	v_mfma_f32_32x32x16_bf16 v[16:31], v[188:191], v[104:107], v[16:31]
	v_fmamk_f32 v32, v32, 0x3e16c740, v163
	v_fmamk_f32 v48, v48, 0x3e16c740, v163
	v_exp_f32_e32 v32, v32
	v_exp_f32_e32 v48, v48
	ds_read_b64_tr_b16 v[196:197], v222 offset:3136
	ds_read_b64_tr_b16 v[198:199], v222 offset:4672
	v_mfma_f32_32x32x16_bf16 v[226:241], v[246:249], v[104:107], v[226:241]
	v_fmamk_f32 v33, v33, 0x3e16c740, v163
	v_fmamk_f32 v49, v49, 0x3e16c740, v163
	v_exp_f32_e32 v33, v33
	v_exp_f32_e32 v49, v49
	ds_read_b64_tr_b16 v[200:201], v222 offset:9216
	ds_read_b64_tr_b16 v[202:203], v222 offset:10752
	s_waitcnt lgkmcnt(9)
	v_mfma_f32_32x32x16_bf16 v[64:79], v[136:139], v[112:115], 0
	v_fmamk_f32 v34, v34, 0x3e16c740, v163
	v_fmamk_f32 v50, v50, 0x3e16c740, v163
	v_exp_f32_e32 v34, v34
	v_exp_f32_e32 v50, v50
	ds_read_b128 v[136:139], v243 offset:13376
	ds_read_b64_tr_b16 v[204:205], v222 offset:9280
	ds_read_b64_tr_b16 v[206:207], v222 offset:10816
	s_waitcnt lgkmcnt(11)
	v_mfma_f32_32x32x16_bf16 v[80:95], v[140:143], v[112:115], 0
	v_cvt_pk_bf16_f32 v96, v32, v33
	v_cvt_pk_bf16_f32 v104, v48, v49
	v_fmamk_f32 v35, v35, 0x3e16c740, v163
	v_fmamk_f32 v51, v51, 0x3e16c740, v163
	ds_read_b128 v[140:143], v243 offset:20032
	s_waitcnt lgkmcnt(11)
	v_mfma_f32_32x32x16_bf16 v[64:79], v[144:147], v[116:119], v[64:79]
	v_exp_f32_e32 v35, v35
	v_exp_f32_e32 v51, v51
	v_fmamk_f32 v36, v36, 0x3e16c740, v163
	v_fmamk_f32 v52, v52, 0x3e16c740, v163
	ds_read_b128 v[144:147], v243 offset:13408
	s_waitcnt lgkmcnt(11)
	v_mfma_f32_32x32x16_bf16 v[80:95], v[148:151], v[116:119], v[80:95]
	v_exp_f32_e32 v36, v36
	v_exp_f32_e32 v52, v52
	v_cvt_pk_bf16_f32 v97, v34, v35
	v_cvt_pk_bf16_f32 v105, v50, v51
	ds_read_b128 v[148:151], v243 offset:20064
	s_waitcnt lgkmcnt(5)
	v_mfma_f32_32x32x16_bf16 v[64:79], v[136:139], v[120:123], v[64:79]
	v_fmamk_f32 v37, v37, 0x3e16c740, v163
	v_fmamk_f32 v53, v53, 0x3e16c740, v163
	v_exp_f32_e32 v37, v37
	v_exp_f32_e32 v53, v53
	ds_read_b128 v[136:139], v243 offset:13440
	s_waitcnt lgkmcnt(3)
	v_mfma_f32_32x32x16_bf16 v[80:95], v[140:143], v[120:123], v[80:95]
	v_fmamk_f32 v38, v38, 0x3e16c740, v163
	v_fmamk_f32 v54, v54, 0x3e16c740, v163
	v_exp_f32_e32 v38, v38
	v_exp_f32_e32 v54, v54
	ds_read_b128 v[140:143], v243 offset:20096
	s_waitcnt lgkmcnt(3)
	v_mfma_f32_32x32x16_bf16 v[64:79], v[144:147], v[124:127], v[64:79]
	v_cvt_pk_bf16_f32 v98, v36, v37
	v_cvt_pk_bf16_f32 v106, v52, v53
	v_fmamk_f32 v39, v39, 0x3e16c740, v163
	v_fmamk_f32 v55, v55, 0x3e16c740, v163
	v_exp_f32_e32 v39, v39
	ds_read_b128 v[144:147], v243 offset:13472
	s_waitcnt lgkmcnt(3)
	v_mfma_f32_32x32x16_bf16 v[80:95], v[148:151], v[124:127], v[80:95]
	v_exp_f32_e32 v55, v55
	v_fmamk_f32 v40, v40, 0x3e16c740, v163
	v_fmamk_f32 v56, v56, 0x3e16c740, v163
	ds_read_b128 v[148:151], v243 offset:20128
	s_waitcnt lgkmcnt(3)
	v_mfma_f32_32x32x16_bf16 v[64:79], v[136:139], v[128:131], v[64:79]
	v_exp_f32_e32 v40, v40
	v_exp_f32_e32 v56, v56
	v_cvt_pk_bf16_f32 v99, v38, v39
	v_cvt_pk_bf16_f32 v107, v54, v55
	s_waitcnt vmcnt(5)
	ds_write_b128 v218, v[152:155]
	s_waitcnt vmcnt(4)
	ds_write_b64 v219, v[160:161]
	s_waitcnt vmcnt(3)
	ds_write_b128 v224, v[156:159]
	s_waitcnt lgkmcnt(5)
	v_mfma_f32_32x32x16_bf16 v[80:95], v[140:143], v[128:131], v[80:95]
	v_fmamk_f32 v41, v41, 0x3e16c740, v163
	v_fmamk_f32 v57, v57, 0x3e16c740, v163
	v_exp_f32_e32 v41, v41
	v_exp_f32_e32 v57, v57
	s_waitcnt lgkmcnt(4)
	v_mfma_f32_32x32x16_bf16 v[64:79], v[144:147], v[132:135], v[64:79]
	v_fmamk_f32 v42, v42, 0x3e16c740, v163
	v_fmamk_f32 v58, v58, 0x3e16c740, v163
	v_exp_f32_e32 v42, v42
	v_exp_f32_e32 v58, v58
	s_waitcnt lgkmcnt(3)
	v_mfma_f32_32x32x16_bf16 v[80:95], v[148:151], v[132:135], v[80:95]
	v_fmamk_f32 v43, v43, 0x3e16c740, v163
	v_fmamk_f32 v59, v59, 0x3e16c740, v163
	v_exp_f32_e32 v43, v43
	v_exp_f32_e32 v59, v59
	v_mfma_f32_32x32x16_bf16 v[0:15], v[192:195], v[100:103], v[0:15]
	v_fmamk_f32 v44, v44, 0x3e16c740, v163
	v_fmamk_f32 v60, v60, 0x3e16c740, v163
	v_exp_f32_e32 v44, v44
	ds_read_b64_tr_b16 v[176:177], v223 offset:0
	ds_read_b64_tr_b16 v[178:179], v223 offset:1536
	v_mfma_f32_32x32x16_bf16 v[16:31], v[196:199], v[100:103], v[16:31]
	v_exp_f32_e32 v60, v60
	v_fmamk_f32 v45, v45, 0x3e16c740, v163
	v_fmamk_f32 v61, v61, 0x3e16c740, v163
	v_exp_f32_e32 v45, v45
	ds_read_b64_tr_b16 v[180:181], v223 offset:64
	ds_read_b64_tr_b16 v[182:183], v223 offset:1600
	v_mfma_f32_32x32x16_bf16 v[226:241], v[246:249], v[100:103], v[226:241]
	v_cvt_pk_bf16_f32 v100, v40, v41
	v_cvt_pk_bf16_f32 v101, v42, v43
	v_exp_f32_e32 v61, v61
	v_fmamk_f32 v46, v46, 0x3e16c740, v163
	v_fmamk_f32 v62, v62, 0x3e16c740, v163
	v_exp_f32_e32 v46, v46
	ds_read_b64_tr_b16 v[184:185], v223 offset:6144
	ds_read_b64_tr_b16 v[186:187], v223 offset:7680
	v_mfma_f32_32x32x16_bf16 v[0:15], v[200:203], v[108:111], v[0:15]
	v_exp_f32_e32 v62, v62
	v_cvt_pk_bf16_f32 v102, v44, v45
	v_fmamk_f32 v47, v47, 0x3e16c740, v163
	v_fmamk_f32 v63, v63, 0x3e16c740, v163
	ds_read_b64_tr_b16 v[188:189], v223 offset:6208
	ds_read_b64_tr_b16 v[190:191], v223 offset:7744
	v_mfma_f32_32x32x16_bf16 v[16:31], v[204:207], v[108:111], v[16:31]
	v_exp_f32_e32 v47, v47
	v_exp_f32_e32 v63, v63
	v_cvt_pk_bf16_f32 v103, v46, v47
	v_mfma_f32_32x32x16_bf16 v[226:241], v[246:249], v[108:111], v[226:241]
	v_cvt_pk_bf16_f32 v108, v56, v57
	v_cvt_pk_bf16_f32 v109, v58, v59
	v_cvt_pk_bf16_f32 v110, v60, v61
	v_cvt_pk_bf16_f32 v111, v62, v63
	s_cmp_lg_u32 s9, 0
	s_cbranch_scc0 .Lamla_noresc_5
	s_nop 15
	v_pk_mul_f32 v[0:1], v[0:1], v[166:167] op_sel_hi:[1,0]
	v_pk_mul_f32 v[2:3], v[2:3], v[166:167] op_sel_hi:[1,0]
	v_pk_mul_f32 v[4:5], v[4:5], v[166:167] op_sel_hi:[1,0]
	v_pk_mul_f32 v[6:7], v[6:7], v[166:167] op_sel_hi:[1,0]
	v_pk_mul_f32 v[8:9], v[8:9], v[166:167] op_sel_hi:[1,0]
	v_pk_mul_f32 v[10:11], v[10:11], v[166:167] op_sel_hi:[1,0]
	v_pk_mul_f32 v[12:13], v[12:13], v[166:167] op_sel_hi:[1,0]
	v_pk_mul_f32 v[14:15], v[14:15], v[166:167] op_sel_hi:[1,0]
	v_pk_mul_f32 v[16:17], v[16:17], v[166:167] op_sel_hi:[1,0]
	v_pk_mul_f32 v[18:19], v[18:19], v[166:167] op_sel_hi:[1,0]
	v_pk_mul_f32 v[20:21], v[20:21], v[166:167] op_sel_hi:[1,0]
	v_pk_mul_f32 v[22:23], v[22:23], v[166:167] op_sel_hi:[1,0]
	v_pk_mul_f32 v[24:25], v[24:25], v[166:167] op_sel_hi:[1,0]
	v_pk_mul_f32 v[26:27], v[26:27], v[166:167] op_sel_hi:[1,0]
	v_pk_mul_f32 v[28:29], v[28:29], v[166:167] op_sel_hi:[1,0]
	v_pk_mul_f32 v[30:31], v[30:31], v[166:167] op_sel_hi:[1,0]
	v_mul_f32_e32 v226, v226, v166

.Lamla_tail:
	ds_read_b128 v[136:139], v243 offset:0
	ds_read_b128 v[140:143], v243 offset:6656
	ds_read_b128 v[144:147], v243 offset:32
	ds_read_b128 v[148:151], v243 offset:6688
	v_mfma_f32_32x32x16_bf16 v[0:15], v[176:179], v[96:99], v[0:15]
	v_max3_f32 v168, v64, v65, v66
	v_max3_f32 v170, v80, v81, v82
	v_max3_f32 v168, v168, v67, v68
	v_max3_f32 v170, v170, v83, v84
	v_max3_f32 v168, v168, v69, v70
	v_max3_f32 v170, v170, v85, v86
	s_mov_b32 s55, s52
	s_mov_b32 s52, s53
	s_mov_b32 s53, s54
	s_mov_b32 s54, s55
	s_mov_b32 s9, 0
	v_mfma_f32_32x32x16_bf16 v[16:31], v[180:183], v[96:99], v[16:31]
	v_max3_f32 v168, v168, v71, v72
	v_max3_f32 v170, v170, v87, v88
	v_max3_f32 v168, v168, v73, v74
	v_max3_f32 v170, v170, v89, v90
	v_max3_f32 v168, v168, v75, v76
	v_max3_f32 v170, v170, v91, v92
	global_load_dwordx4 v[156:159], v225, s[4:5]
	s_add_u32 s4, s4, 0x2000
	s_addc_u32 s5, s5, 0
	v_add_u32_e32 v222, s53, v220
	v_add_u32_e32 v224, s54, v221
	v_mfma_f32_32x32x16_bf16 v[226:241], v[246:249], v[96:99], v[226:241]
	v_max3_f32 v168, v168, v77, v78
	v_max3_f32 v170, v170, v93, v94
	v_max_f32_e32 v168, v168, v79
	v_max_f32_e32 v170, v170, v95
	v_max_f32_e32 v168, v168, v170
	v_mfma_f32_32x32x16_bf16 v[0:15], v[184:187], v[104:107], v[0:15]
	v_mov_b32_e32 v170, v168
	s_nop 1
	v_permlane32_swap_b32_e32 v168, v170
	v_max_f32_e32 v168, v168, v170
	v_mul_f32_e32 v168, 0x3e16c740, v168
	v_cmp_gt_f32_e32 vcc, v168, v164
	s_cbranch_vccz .Lamla_nors_6
	v_max_f32_e32 v170, v162, v168
	v_sub_f32_e32 v166, v162, v170
	v_exp_f32_e32 v166, v166
	v_mov_b32_e32 v162, v170
	v_add_f32_e32 v164, 0x41000000, v170
	v_xor_b32_e32 v163, 0x80000000, v170
	s_mov_b32 s9, 1
.Lamla_nors_6:
	ds_read_b64_tr_b16 v[192:193], v223 offset:3072
	ds_read_b64_tr_b16 v[194:195], v223 offset:4608
	v_mfma_f32_32x32x16_bf16 v[16:31], v[188:191], v[104:107], v[16:31]
	v_fmamk_f32 v64, v64, 0x3e16c740, v163
	v_fmamk_f32 v80, v80, 0x3e16c740, v163
	v_exp_f32_e32 v64, v64
	v_exp_f32_e32 v80, v80
	ds_read_b64_tr_b16 v[196:197], v223 offset:3136
	ds_read_b64_tr_b16 v[198:199], v223 offset:4672
	v_mfma_f32_32x32x16_bf16 v[226:241], v[246:249], v[104:107], v[226:241]
	v_fmamk_f32 v65, v65, 0x3e16c740, v163
	v_fmamk_f32 v81, v81, 0x3e16c740, v163
	v_exp_f32_e32 v65, v65
	v_exp_f32_e32 v81, v81
	ds_read_b64_tr_b16 v[200:201], v223 offset:9216
	ds_read_b64_tr_b16 v[202:203], v223 offset:10752
	s_waitcnt lgkmcnt(9)
	v_mfma_f32_32x32x16_bf16 v[32:47], v[136:139], v[112:115], 0
	v_fmamk_f32 v66, v66, 0x3e16c740, v163
	v_fmamk_f32 v82, v82, 0x3e16c740, v163
	v_exp_f32_e32 v66, v66
	v_exp_f32_e32 v82, v82
	ds_read_b128 v[136:139], v243 offset:64
	ds_read_b64_tr_b16 v[204:205], v223 offset:9280
	ds_read_b64_tr_b16 v[206:207], v223 offset:10816
	s_waitcnt lgkmcnt(11)
	v_mfma_f32_32x32x16_bf16 v[48:63], v[140:143], v[112:115], 0
	v_cvt_pk_bf16_f32 v96, v64, v65
	v_cvt_pk_bf16_f32 v104, v80, v81
	v_fmamk_f32 v67, v67, 0x3e16c740, v163
	v_fmamk_f32 v83, v83, 0x3e16c740, v163
	ds_read_b128 v[140:143], v243 offset:6720
	s_waitcnt lgkmcnt(11)
	v_mfma_f32_32x32x16_bf16 v[32:47], v[144:147], v[116:119], v[32:47]
	v_exp_f32_e32 v67, v67
	v_exp_f32_e32 v83, v83
	v_fmamk_f32 v68, v68, 0x3e16c740, v163
	v_fmamk_f32 v84, v84, 0x3e16c740, v163
	ds_read_b128 v[144:147], v243 offset:96
	s_waitcnt lgkmcnt(11)
	v_mfma_f32_32x32x16_bf16 v[48:63], v[148:151], v[116:119], v[48:63]
	v_exp_f32_e32 v68, v68
	v_exp_f32_e32 v84, v84
	v_cvt_pk_bf16_f32 v97, v66, v67
	v_cvt_pk_bf16_f32 v105, v82, v83
	ds_read_b128 v[148:151], v243 offset:6752
	s_waitcnt lgkmcnt(5)
	v_mfma_f32_32x32x16_bf16 v[32:47], v[136:139], v[120:123], v[32:47]
	v_fmamk_f32 v69, v69, 0x3e16c740, v163
	v_fmamk_f32 v85, v85, 0x3e16c740, v163
	v_exp_f32_e32 v69, v69
	v_exp_f32_e32 v85, v85
	ds_read_b128 v[136:139], v243 offset:128
	s_waitcnt lgkmcnt(3)
	v_mfma_f32_32x32x16_bf16 v[48:63], v[140:143], v[120:123], v[48:63]
	v_fmamk_f32 v70, v70, 0x3e16c740, v163
	v_fmamk_f32 v86, v86, 0x3e16c740, v163
	v_exp_f32_e32 v70, v70
	v_exp_f32_e32 v86, v86
	ds_read_b128 v[140:143], v243 offset:6784
	s_waitcnt lgkmcnt(3)
	v_mfma_f32_32x32x16_bf16 v[32:47], v[144:147], v[124:127], v[32:47]
	v_cvt_pk_bf16_f32 v98, v68, v69
	v_cvt_pk_bf16_f32 v106, v84, v85
	v_fmamk_f32 v71, v71, 0x3e16c740, v163
	v_fmamk_f32 v87, v87, 0x3e16c740, v163
	v_exp_f32_e32 v71, v71
	ds_read_b128 v[144:147], v243 offset:160
	s_waitcnt lgkmcnt(3)
	v_mfma_f32_32x32x16_bf16 v[48:63], v[148:151], v[124:127], v[48:63]
	v_exp_f32_e32 v87, v87
	v_fmamk_f32 v72, v72, 0x3e16c740, v163
	v_fmamk_f32 v88, v88, 0x3e16c740, v163
	ds_read_b128 v[148:151], v243 offset:6816
	s_waitcnt lgkmcnt(3)
	v_mfma_f32_32x32x16_bf16 v[32:47], v[136:139], v[128:131], v[32:47]
	v_exp_f32_e32 v72, v72
	v_exp_f32_e32 v88, v88
	v_cvt_pk_bf16_f32 v99, v70, v71
	v_cvt_pk_bf16_f32 v107, v86, v87
	s_waitcnt vmcnt(3)
	ds_write_b128 v218, v[208:211] offset:13312
	s_waitcnt vmcnt(2)
	ds_write_b64 v219, v[216:217] offset:13312
	s_waitcnt vmcnt(1)
	ds_write_b128 v224, v[212:215]
	s_waitcnt lgkmcnt(5)
	v_mfma_f32_32x32x16_bf16 v[48:63], v[140:143], v[128:131], v[48:63]
	v_fmamk_f32 v73, v73, 0x3e16c740, v163
	v_fmamk_f32 v89, v89, 0x3e16c740, v163
	v_exp_f32_e32 v73, v73
	v_exp_f32_e32 v89, v89
	s_waitcnt lgkmcnt(4)
	v_mfma_f32_32x32x16_bf16 v[32:47], v[144:147], v[132:135], v[32:47]
	v_fmamk_f32 v74, v74, 0x3e16c740, v163
	v_fmamk_f32 v90, v90, 0x3e16c740, v163
	v_exp_f32_e32 v74, v74
	v_exp_f32_e32 v90, v90
	s_waitcnt lgkmcnt(3)
	v_mfma_f32_32x32x16_bf16 v[48:63], v[148:151], v[132:135], v[48:63]
	v_fmamk_f32 v75, v75, 0x3e16c740, v163
	v_fmamk_f32 v91, v91, 0x3e16c740, v163
	v_exp_f32_e32 v75, v75
	v_exp_f32_e32 v91, v91
	v_mfma_f32_32x32x16_bf16 v[0:15], v[192:195], v[100:103], v[0:15]
	v_fmamk_f32 v76, v76, 0x3e16c740, v163
	v_fmamk_f32 v92, v92, 0x3e16c740, v163
	v_exp_f32_e32 v76, v76
	ds_read_b64_tr_b16 v[176:177], v222 offset:0
	ds_read_b64_tr_b16 v[178:179], v222 offset:1536
	v_mfma_f32_32x32x16_bf16 v[16:31], v[196:199], v[100:103], v[16:31]
	v_exp_f32_e32 v92, v92
	v_fmamk_f32 v77, v77, 0x3e16c740, v163
	v_fmamk_f32 v93, v93, 0x3e16c740, v163
	v_exp_f32_e32 v77, v77
	ds_read_b64_tr_b16 v[180:181], v222 offset:64
	ds_read_b64_tr_b16 v[182:183], v222 offset:1600
	v_mfma_f32_32x32x16_bf16 v[226:241], v[246:249], v[100:103], v[226:241]
	v_cvt_pk_bf16_f32 v100, v72, v73
	v_cvt_pk_bf16_f32 v101, v74, v75
	v_exp_f32_e32 v93, v93
	v_fmamk_f32 v78, v78, 0x3e16c740, v163
	v_fmamk_f32 v94, v94, 0x3e16c740, v163
	v_exp_f32_e32 v78, v78
	ds_read_b64_tr_b16 v[184:185], v222 offset:6144
	ds_read_b64_tr_b16 v[186:187], v222 offset:7680
	v_mfma_f32_32x32x16_bf16 v[0:15], v[200:203], v[108:111], v[0:15]
	v_exp_f32_e32 v94, v94
	v_cvt_pk_bf16_f32 v102, v76, v77
	v_fmamk_f32 v79, v79, 0x3e16c740, v163
	v_fmamk_f32 v95, v95, 0x3e16c740, v163
	ds_read_b64_tr_b16 v[188:189], v222 offset:6208
	ds_read_b64_tr_b16 v[190:191], v222 offset:7744
	v_mfma_f32_32x32x16_bf16 v[16:31], v[204:207], v[108:111], v[16:31]
	v_exp_f32_e32 v79, v79
	v_exp_f32_e32 v95, v95
	v_cvt_pk_bf16_f32 v103, v78, v79
	v_mfma_f32_32x32x16_bf16 v[226:241], v[246:249], v[108:111], v[226:241]
	v_cvt_pk_bf16_f32 v108, v88, v89
	v_cvt_pk_bf16_f32 v109, v90, v91
	v_cvt_pk_bf16_f32 v110, v92, v93
	v_cvt_pk_bf16_f32 v111, v94, v95
	s_cmp_lg_u32 s9, 0
	s_cbranch_scc0 .Lamla_noresc_7
	s_nop 15
	v_pk_mul_f32 v[0:1], v[0:1], v[166:167] op_sel_hi:[1,0]
	v_pk_mul_f32 v[2:3], v[2:3], v[166:167] op_sel_hi:[1,0]
	v_pk_mul_f32 v[4:5], v[4:5], v[166:167] op_sel_hi:[1,0]
	v_pk_mul_f32 v[6:7], v[6:7], v[166:167] op_sel_hi:[1,0]
	v_pk_mul_f32 v[8:9], v[8:9], v[166:167] op_sel_hi:[1,0]
	v_pk_mul_f32 v[10:11], v[10:11], v[166:167] op_sel_hi:[1,0]
	v_pk_mul_f32 v[12:13], v[12:13], v[166:167] op_sel_hi:[1,0]
	v_pk_mul_f32 v[14:15], v[14:15], v[166:167] op_sel_hi:[1,0]
	v_pk_mul_f32 v[16:17], v[16:17], v[166:167] op_sel_hi:[1,0]
	v_pk_mul_f32 v[18:19], v[18:19], v[166:167] op_sel_hi:[1,0]
	v_pk_mul_f32 v[20:21], v[20:21], v[166:167] op_sel_hi:[1,0]
	v_pk_mul_f32 v[22:23], v[22:23], v[166:167] op_sel_hi:[1,0]
	v_pk_mul_f32 v[24:25], v[24:25], v[166:167] op_sel_hi:[1,0]
	v_pk_mul_f32 v[26:27], v[26:27], v[166:167] op_sel_hi:[1,0]
	v_pk_mul_f32 v[28:29], v[28:29], v[166:167] op_sel_hi:[1,0]
	v_pk_mul_f32 v[30:31], v[30:31], v[166:167] op_sel_hi:[1,0]
	v_mul_f32_e32 v226, v226, v166
.Lamla_noresc_7:
	s_waitcnt lgkmcnt(0)
	s_barrier
	ds_read_b128 v[136:139], v243 offset:13312
	ds_read_b128 v[140:143], v243 offset:19968
	ds_read_b128 v[144:147], v243 offset:13344
	ds_read_b128 v[148:151], v243 offset:20000
	v_mfma_f32_32x32x16_bf16 v[0:15], v[176:179], v[96:99], v[0:15]
	v_max3_f32 v168, v32, v33, v34
	v_max3_f32 v170, v48, v49, v50
	v_max3_f32 v168, v168, v35, v36
	v_max3_f32 v170, v170, v51, v52
	v_max3_f32 v168, v168, v37, v38
	v_max3_f32 v170, v170, v53, v54
	s_mov_b32 s55, s52
	s_mov_b32 s52, s53
	s_mov_b32 s53, s54
	s_mov_b32 s54, s55
	s_mov_b32 s9, 0
	v_mfma_f32_32x32x16_bf16 v[16:31], v[180:183], v[96:99], v[16:31]
	v_max3_f32 v168, v168, v39, v40
	v_max3_f32 v170, v170, v55, v56
	v_max3_f32 v168, v168, v41, v42
	v_max3_f32 v170, v170, v57, v58
	v_max3_f32 v168, v168, v43, v44
	v_max3_f32 v170, v170, v59, v60
	v_add_u32_e32 v223, s53, v220
	v_add_u32_e32 v224, s54, v221
	v_mfma_f32_32x32x16_bf16 v[226:241], v[246:249], v[96:99], v[226:241]
	v_max3_f32 v168, v168, v45, v46
	v_max3_f32 v170, v170, v61, v62
	v_max_f32_e32 v168, v168, v47
	v_max_f32_e32 v170, v170, v63
	v_max_f32_e32 v168, v168, v170
	v_mfma_f32_32x32x16_bf16 v[0:15], v[184:187], v[104:107], v[0:15]
	v_mov_b32_e32 v170, v168
	s_nop 1
	v_permlane32_swap_b32_e32 v168, v170
	v_max_f32_e32 v168, v168, v170
	v_mul_f32_e32 v168, 0x3e16c740, v168
	v_cmp_gt_f32_e32 vcc, v168, v164
	s_cbranch_vccz .Lamla_nors_8
	v_max_f32_e32 v170, v162, v168
	v_sub_f32_e32 v166, v162, v170
	v_exp_f32_e32 v166, v166
	v_mov_b32_e32 v162, v170
	v_add_f32_e32 v164, 0x41000000, v170
	v_xor_b32_e32 v163, 0x80000000, v170
	s_mov_b32 s9, 1
.Lamla_nors_8:
	ds_read_b64_tr_b16 v[192:193], v222 offset:3072
	ds_read_b64_tr_b16 v[194:195], v222 offset:4608
	v_mfma_f32_32x32x16_bf16 v[16:31], v[188:191], v[104:107], v[16:31]
	v_fmamk_f32 v32, v32, 0x3e16c740, v163
	v_fmamk_f32 v48, v48, 0x3e16c740, v163
	v_exp_f32_e32 v32, v32
	v_exp_f32_e32 v48, v48
	ds_read_b64_tr_b16 v[196:197], v222 offset:3136
	ds_read_b64_tr_b16 v[198:199], v222 offset:4672
	v_mfma_f32_32x32x16_bf16 v[226:241], v[246:249], v[104:107], v[226:241]
	v_fmamk_f32 v33, v33, 0x3e16c740, v163
	v_fmamk_f32 v49, v49, 0x3e16c740, v163
	v_exp_f32_e32 v33, v33
	v_exp_f32_e32 v49, v49
	ds_read_b64_tr_b16 v[200:201], v222 offset:9216
	ds_read_b64_tr_b16 v[202:203], v222 offset:10752
	s_waitcnt lgkmcnt(9)
	v_mfma_f32_32x32x16_bf16 v[64:79], v[136:139], v[112:115], 0
	v_fmamk_f32 v34, v34, 0x3e16c740, v163
	v_fmamk_f32 v50, v50, 0x3e16c740, v163
	v_exp_f32_e32 v34, v34
	v_exp_f32_e32 v50, v50
	ds_read_b128 v[136:139], v243 offset:13376
	ds_read_b64_tr_b16 v[204:205], v222 offset:9280
	ds_read_b64_tr_b16 v[206:207], v222 offset:10816
	s_waitcnt lgkmcnt(11)
	v_mfma_f32_32x32x16_bf16 v[80:95], v[140:143], v[112:115], 0
	v_cvt_pk_bf16_f32 v96, v32, v33
	v_cvt_pk_bf16_f32 v104, v48, v49
	v_fmamk_f32 v35, v35, 0x3e16c740, v163
	v_fmamk_f32 v51, v51, 0x3e16c740, v163
	ds_read_b128 v[140:143], v243 offset:20032
	s_waitcnt lgkmcnt(11)
	v_mfma_f32_32x32x16_bf16 v[64:79], v[144:147], v[116:119], v[64:79]
	v_exp_f32_e32 v35, v35
	v_exp_f32_e32 v51, v51
	v_fmamk_f32 v36, v36, 0x3e16c740, v163
	v_fmamk_f32 v52, v52, 0x3e16c740, v163
	ds_read_b128 v[144:147], v243 offset:13408
	s_waitcnt lgkmcnt(11)
	v_mfma_f32_32x32x16_bf16 v[80:95], v[148:151], v[116:119], v[80:95]
	v_exp_f32_e32 v36, v36
	v_exp_f32_e32 v52, v52
	v_cvt_pk_bf16_f32 v97, v34, v35
	v_cvt_pk_bf16_f32 v105, v50, v51
	ds_read_b128 v[148:151], v243 offset:20064
	s_waitcnt lgkmcnt(5)
	v_mfma_f32_32x32x16_bf16 v[64:79], v[136:139], v[120:123], v[64:79]
	v_fmamk_f32 v37, v37, 0x3e16c740, v163
	v_fmamk_f32 v53, v53, 0x3e16c740, v163
	v_exp_f32_e32 v37, v37
	v_exp_f32_e32 v53, v53
	ds_read_b128 v[136:139], v243 offset:13440
	s_waitcnt lgkmcnt(3)
	v_mfma_f32_32x32x16_bf16 v[80:95], v[140:143], v[120:123], v[80:95]
	v_fmamk_f32 v38, v38, 0x3e16c740, v163
	v_fmamk_f32 v54, v54, 0x3e16c740, v163
	v_exp_f32_e32 v38, v38
	v_exp_f32_e32 v54, v54
	ds_read_b128 v[140:143], v243 offset:20096
	s_waitcnt lgkmcnt(3)
	v_mfma_f32_32x32x16_bf16 v[64:79], v[144:147], v[124:127], v[64:79]
	v_cvt_pk_bf16_f32 v98, v36, v37
	v_cvt_pk_bf16_f32 v106, v52, v53
	v_fmamk_f32 v39, v39, 0x3e16c740, v163
	v_fmamk_f32 v55, v55, 0x3e16c740, v163
	v_exp_f32_e32 v39, v39
	ds_read_b128 v[144:147], v243 offset:13472
	s_waitcnt lgkmcnt(3)
	v_mfma_f32_32x32x16_bf16 v[80:95], v[148:151], v[124:127], v[80:95]
	v_exp_f32_e32 v55, v55
	v_fmamk_f32 v40, v40, 0x3e16c740, v163
	v_fmamk_f32 v56, v56, 0x3e16c740, v163
	ds_read_b128 v[148:151], v243 offset:20128
	s_waitcnt lgkmcnt(3)
	v_mfma_f32_32x32x16_bf16 v[64:79], v[136:139], v[128:131], v[64:79]
	v_exp_f32_e32 v40, v40
	v_exp_f32_e32 v56, v56
	v_cvt_pk_bf16_f32 v99, v38, v39
	v_cvt_pk_bf16_f32 v107, v54, v55
	s_waitcnt vmcnt(0)
	ds_write_b128 v224, v[156:159]
	s_waitcnt lgkmcnt(3)
	v_mfma_f32_32x32x16_bf16 v[80:95], v[140:143], v[128:131], v[80:95]
	v_fmamk_f32 v41, v41, 0x3e16c740, v163
	v_fmamk_f32 v57, v57, 0x3e16c740, v163
	v_exp_f32_e32 v41, v41
	v_exp_f32_e32 v57, v57
	s_waitcnt lgkmcnt(2)
	v_mfma_f32_32x32x16_bf16 v[64:79], v[144:147], v[132:135], v[64:79]
	v_fmamk_f32 v42, v42, 0x3e16c740, v163
	v_fmamk_f32 v58, v58, 0x3e16c740, v163
	v_exp_f32_e32 v42, v42
	v_exp_f32_e32 v58, v58
	s_waitcnt lgkmcnt(1)
	v_mfma_f32_32x32x16_bf16 v[80:95], v[148:151], v[132:135], v[80:95]
	v_fmamk_f32 v43, v43, 0x3e16c740, v163
	v_fmamk_f32 v59, v59, 0x3e16c740, v163
	v_exp_f32_e32 v43, v43
	v_exp_f32_e32 v59, v59
	v_mfma_f32_32x32x16_bf16 v[0:15], v[192:195], v[100:103], v[0:15]
	v_fmamk_f32 v44, v44, 0x3e16c740, v163
	v_fmamk_f32 v60, v60, 0x3e16c740, v163
	v_exp_f32_e32 v44, v44
	ds_read_b64_tr_b16 v[176:177], v223 offset:0
	ds_read_b64_tr_b16 v[178:179], v223 offset:1536
	v_mfma_f32_32x32x16_bf16 v[16:31], v[196:199], v[100:103], v[16:31]
	v_exp_f32_e32 v60, v60
	v_fmamk_f32 v45, v45, 0x3e16c740, v163
	v_fmamk_f32 v61, v61, 0x3e16c740, v163
	v_exp_f32_e32 v45, v45
	ds_read_b64_tr_b16 v[180:181], v223 offset:64
	ds_read_b64_tr_b16 v[182:183], v223 offset:1600
	v_mfma_f32_32x32x16_bf16 v[226:241], v[246:249], v[100:103], v[226:241]
	v_cvt_pk_bf16_f32 v100, v40, v41
	v_cvt_pk_bf16_f32 v101, v42, v43
	v_exp_f32_e32 v61, v61
	v_fmamk_f32 v46, v46, 0x3e16c740, v163
	v_fmamk_f32 v62, v62, 0x3e16c740, v163
	v_exp_f32_e32 v46, v46
	ds_read_b64_tr_b16 v[184:185], v223 offset:6144
	ds_read_b64_tr_b16 v[186:187], v223 offset:7680
	v_mfma_f32_32x32x16_bf16 v[0:15], v[200:203], v[108:111], v[0:15]
	v_exp_f32_e32 v62, v62
	v_cvt_pk_bf16_f32 v102, v44, v45
	v_fmamk_f32 v47, v47, 0x3e16c740, v163
	v_fmamk_f32 v63, v63, 0x3e16c740, v163
	ds_read_b64_tr_b16 v[188:189], v223 offset:6208
	ds_read_b64_tr_b16 v[190:191], v223 offset:7744
	v_mfma_f32_32x32x16_bf16 v[16:31], v[204:207], v[108:111], v[16:31]
	v_exp_f32_e32 v47, v47
	v_exp_f32_e32 v63, v63
	v_cvt_pk_bf16_f32 v103, v46, v47
	v_mfma_f32_32x32x16_bf16 v[226:241], v[246:249], v[108:111], v[226:241]
	v_cvt_pk_bf16_f32 v108, v56, v57
	v_cvt_pk_bf16_f32 v109, v58, v59
	v_cvt_pk_bf16_f32 v110, v60, v61
	v_cvt_pk_bf16_f32 v111, v62, v63
	s_cmp_lg_u32 s9, 0
	s_cbranch_scc0 .Lamla_noresc_9
	s_nop 15
	v_pk_mul_f32 v[0:1], v[0:1], v[166:167] op_sel_hi:[1,0]
	v_pk_mul_f32 v[2:3], v[2:3], v[166:167] op_sel_hi:[1,0]
	v_pk_mul_f32 v[4:5], v[4:5], v[166:167] op_sel_hi:[1,0]
	v_pk_mul_f32 v[6:7], v[6:7], v[166:167] op_sel_hi:[1,0]
	v_pk_mul_f32 v[8:9], v[8:9], v[166:167] op_sel_hi:[1,0]
	v_pk_mul_f32 v[10:11], v[10:11], v[166:167] op_sel_hi:[1,0]
	v_pk_mul_f32 v[12:13], v[12:13], v[166:167] op_sel_hi:[1,0]
	v_pk_mul_f32 v[14:15], v[14:15], v[166:167] op_sel_hi:[1,0]
	v_pk_mul_f32 v[16:17], v[16:17], v[166:167] op_sel_hi:[1,0]
	v_pk_mul_f32 v[18:19], v[18:19], v[166:167] op_sel_hi:[1,0]
	v_pk_mul_f32 v[20:21], v[20:21], v[166:167] op_sel_hi:[1,0]
	v_pk_mul_f32 v[22:23], v[22:23], v[166:167] op_sel_hi:[1,0]
	v_pk_mul_f32 v[24:25], v[24:25], v[166:167] op_sel_hi:[1,0]
	v_pk_mul_f32 v[26:27], v[26:27], v[166:167] op_sel_hi:[1,0]
	v_pk_mul_f32 v[28:29], v[28:29], v[166:167] op_sel_hi:[1,0]
	v_pk_mul_f32 v[30:31], v[30:31], v[166:167] op_sel_hi:[1,0]
	v_mul_f32_e32 v226, v226, v166
.Lamla_noresc_9:
	s_waitcnt lgkmcnt(0)
	s_barrier
	ds_read_b64_tr_b16 v[192:193], v223 offset:3072
	ds_read_b64_tr_b16 v[194:195], v223 offset:4608
	ds_read_b64_tr_b16 v[196:197], v223 offset:3136
	ds_read_b64_tr_b16 v[198:199], v223 offset:4672
	v_mfma_f32_32x32x16_bf16 v[0:15], v[176:179], v[96:99], v[0:15]
	v_max3_f32 v168, v64, v65, v66
	v_max3_f32 v170, v80, v81, v82
	v_max3_f32 v168, v168, v67, v68
	v_max3_f32 v170, v170, v83, v84
	v_max3_f32 v168, v168, v69, v70
	v_max3_f32 v170, v170, v85, v86
	v_max3_f32 v168, v168, v71, v72
	v_max3_f32 v170, v170, v87, v88
	v_max3_f32 v168, v168, v73, v74
	v_max3_f32 v170, v170, v89, v90
	v_max3_f32 v168, v168, v75, v76
	v_max3_f32 v170, v170, v91, v92
	s_mov_b32 s55, s52
	s_mov_b32 s52, s53
	s_mov_b32 s53, s54
	s_mov_b32 s54, s55
	s_mov_b32 s9, 0
	ds_read_b64_tr_b16 v[200:201], v223 offset:9216
	ds_read_b64_tr_b16 v[202:203], v223 offset:10752
	ds_read_b64_tr_b16 v[204:205], v223 offset:9280
	ds_read_b64_tr_b16 v[206:207], v223 offset:10816
	v_mfma_f32_32x32x16_bf16 v[16:31], v[180:183], v[96:99], v[16:31]
	v_max3_f32 v168, v168, v77, v78
	v_max3_f32 v170, v170, v93, v94
	v_max_f32_e32 v168, v168, v79
	v_max_f32_e32 v170, v170, v95
	v_max_f32_e32 v168, v168, v170
	v_mov_b32_e32 v170, v168
	s_nop 1
	v_permlane32_swap_b32_e32 v168, v170
	v_max_f32_e32 v168, v168, v170
	v_mul_f32_e32 v168, 0x3e16c740, v168
	v_cmp_gt_f32_e32 vcc, v168, v164
	s_cbranch_vccz .Lamla_nors_10
	v_max_f32_e32 v170, v162, v168
	v_sub_f32_e32 v166, v162, v170
	v_exp_f32_e32 v166, v166
	v_mov_b32_e32 v162, v170
	v_add_f32_e32 v164, 0x41000000, v170
	v_xor_b32_e32 v163, 0x80000000, v170
	s_mov_b32 s9, 1
.Lamla_nors_10:
	v_add_u32_e32 v222, s53, v220
	v_mfma_f32_32x32x16_bf16 v[226:241], v[246:249], v[96:99], v[226:241]
	v_fmamk_f32 v64, v64, 0x3e16c740, v163
	v_fmamk_f32 v80, v80, 0x3e16c740, v163
	v_exp_f32_e32 v64, v64
	v_exp_f32_e32 v80, v80
	v_fmamk_f32 v65, v65, 0x3e16c740, v163
	v_fmamk_f32 v81, v81, 0x3e16c740, v163
	v_exp_f32_e32 v65, v65
	v_exp_f32_e32 v81, v81
	v_mfma_f32_32x32x16_bf16 v[0:15], v[184:187], v[104:107], v[0:15]
	v_fmamk_f32 v66, v66, 0x3e16c740, v163
	v_fmamk_f32 v82, v82, 0x3e16c740, v163
	v_exp_f32_e32 v66, v66
	v_exp_f32_e32 v82, v82
	v_cvt_pk_bf16_f32 v96, v64, v65
	v_fmamk_f32 v67, v67, 0x3e16c740, v163
	v_fmamk_f32 v83, v83, 0x3e16c740, v163
	v_exp_f32_e32 v67, v67
	v_mfma_f32_32x32x16_bf16 v[16:31], v[188:191], v[104:107], v[16:31]
	v_exp_f32_e32 v83, v83
	v_fmamk_f32 v68, v68, 0x3e16c740, v163
	v_fmamk_f32 v84, v84, 0x3e16c740, v163
	v_exp_f32_e32 v68, v68
	v_exp_f32_e32 v84, v84
	v_cvt_pk_bf16_f32 v97, v66, v67
	v_fmamk_f32 v69, v69, 0x3e16c740, v163
	v_fmamk_f32 v85, v85, 0x3e16c740, v163
	v_mfma_f32_32x32x16_bf16 v[226:241], v[246:249], v[104:107], v[226:241]
	v_cvt_pk_bf16_f32 v104, v80, v81
	v_cvt_pk_bf16_f32 v105, v82, v83
	v_exp_f32_e32 v69, v69
	v_exp_f32_e32 v85, v85
	v_fmamk_f32 v70, v70, 0x3e16c740, v163
	v_fmamk_f32 v86, v86, 0x3e16c740, v163
	v_exp_f32_e32 v70, v70
	v_exp_f32_e32 v86, v86
	v_cvt_pk_bf16_f32 v98, v68, v69
	s_waitcnt lgkmcnt(6)
	v_mfma_f32_32x32x16_bf16 v[0:15], v[192:195], v[100:103], v[0:15]
	v_cvt_pk_bf16_f32 v106, v84, v85
	v_fmamk_f32 v71, v71, 0x3e16c740, v163
	v_fmamk_f32 v87, v87, 0x3e16c740, v163
	v_exp_f32_e32 v71, v71
	v_exp_f32_e32 v87, v87
	v_fmamk_f32 v72, v72, 0x3e16c740, v163
	v_fmamk_f32 v88, v88, 0x3e16c740, v163
	v_exp_f32_e32 v72, v72
	ds_read_b64_tr_b16 v[176:177], v222 offset:0
	ds_read_b64_tr_b16 v[178:179], v222 offset:1536
	s_waitcnt lgkmcnt(6)
	v_mfma_f32_32x32x16_bf16 v[16:31], v[196:199], v[100:103], v[16:31]
	v_exp_f32_e32 v88, v88
	v_cvt_pk_bf16_f32 v99, v70, v71
	v_cvt_pk_bf16_f32 v107, v86, v87
	v_fmamk_f32 v73, v73, 0x3e16c740, v163
	v_fmamk_f32 v89, v89, 0x3e16c740, v163
	v_exp_f32_e32 v73, v73
	v_exp_f32_e32 v89, v89
	v_fmamk_f32 v74, v74, 0x3e16c740, v163
	ds_read_b64_tr_b16 v[180:181], v222 offset:64
	ds_read_b64_tr_b16 v[182:183], v222 offset:1600
	v_mfma_f32_32x32x16_bf16 v[226:241], v[246:249], v[100:103], v[226:241]
	v_fmamk_f32 v90, v90, 0x3e16c740, v163
	v_exp_f32_e32 v74, v74
	v_exp_f32_e32 v90, v90
	v_cvt_pk_bf16_f32 v100, v72, v73
	v_fmamk_f32 v75, v75, 0x3e16c740, v163
	v_fmamk_f32 v91, v91, 0x3e16c740, v163
	v_exp_f32_e32 v75, v75
	v_exp_f32_e32 v91, v91
	ds_read_b64_tr_b16 v[184:185], v222 offset:6144
	ds_read_b64_tr_b16 v[186:187], v222 offset:7680
	s_waitcnt lgkmcnt(8)
	v_mfma_f32_32x32x16_bf16 v[0:15], v[200:203], v[108:111], v[0:15]
	v_fmamk_f32 v76, v76, 0x3e16c740, v163
	v_fmamk_f32 v92, v92, 0x3e16c740, v163
	v_exp_f32_e32 v76, v76
	v_exp_f32_e32 v92, v92
	v_cvt_pk_bf16_f32 v101, v74, v75
	v_fmamk_f32 v77, v77, 0x3e16c740, v163
	v_fmamk_f32 v93, v93, 0x3e16c740, v163
	v_exp_f32_e32 v77, v77
	ds_read_b64_tr_b16 v[188:189], v222 offset:6208
	ds_read_b64_tr_b16 v[190:191], v222 offset:7744
	s_waitcnt lgkmcnt(8)
	v_mfma_f32_32x32x16_bf16 v[16:31], v[204:207], v[108:111], v[16:31]
	v_exp_f32_e32 v93, v93
	v_fmamk_f32 v78, v78, 0x3e16c740, v163
	v_fmamk_f32 v94, v94, 0x3e16c740, v163
	v_exp_f32_e32 v78, v78
	v_exp_f32_e32 v94, v94
	v_cvt_pk_bf16_f32 v102, v76, v77
	v_fmamk_f32 v79, v79, 0x3e16c740, v163
	v_fmamk_f32 v95, v95, 0x3e16c740, v163
	v_mfma_f32_32x32x16_bf16 v[226:241], v[246:249], v[108:111], v[226:241]
	v_cvt_pk_bf16_f32 v108, v88, v89
	v_cvt_pk_bf16_f32 v109, v90, v91
	v_cvt_pk_bf16_f32 v110, v92, v93
	v_exp_f32_e32 v79, v79
	v_exp_f32_e32 v95, v95
	v_cvt_pk_bf16_f32 v103, v78, v79
	v_cvt_pk_bf16_f32 v111, v94, v95
	s_cmp_lg_u32 s9, 0
	s_cbranch_scc0 .Lamla_noresc_11
	s_nop 15
	v_pk_mul_f32 v[0:1], v[0:1], v[166:167] op_sel_hi:[1,0]
	v_pk_mul_f32 v[2:3], v[2:3], v[166:167] op_sel_hi:[1,0]
	v_pk_mul_f32 v[4:5], v[4:5], v[166:167] op_sel_hi:[1,0]
	v_pk_mul_f32 v[6:7], v[6:7], v[166:167] op_sel_hi:[1,0]
	v_pk_mul_f32 v[8:9], v[8:9], v[166:167] op_sel_hi:[1,0]
	v_pk_mul_f32 v[10:11], v[10:11], v[166:167] op_sel_hi:[1,0]
	v_pk_mul_f32 v[12:13], v[12:13], v[166:167] op_sel_hi:[1,0]
	v_pk_mul_f32 v[14:15], v[14:15], v[166:167] op_sel_hi:[1,0]
	v_pk_mul_f32 v[16:17], v[16:17], v[166:167] op_sel_hi:[1,0]
	v_pk_mul_f32 v[18:19], v[18:19], v[166:167] op_sel_hi:[1,0]
	v_pk_mul_f32 v[20:21], v[20:21], v[166:167] op_sel_hi:[1,0]
	v_pk_mul_f32 v[22:23], v[22:23], v[166:167] op_sel_hi:[1,0]
	v_pk_mul_f32 v[24:25], v[24:25], v[166:167] op_sel_hi:[1,0]
	v_pk_mul_f32 v[26:27], v[26:27], v[166:167] op_sel_hi:[1,0]
	v_pk_mul_f32 v[28:29], v[28:29], v[166:167] op_sel_hi:[1,0]
	v_pk_mul_f32 v[30:31], v[30:31], v[166:167] op_sel_hi:[1,0]
	v_mul_f32_e32 v226, v226, v166
; #define AT_PK4(OX, jg) u32x2 { pk_bf16(OX[4 * (jg)] * inv, OX[4 * (jg) + 1] * inv), pk_bf16(OX[4 * (jg) + 2] * inv, OX[4 * (jg) + 3] * inv) }
; template <bool MLA>
; DI void attn_phase(const int TID, const int BID, LAS unsigned char* lds, const Params& p, bool need_ctx) {
;     ...
;         __builtin_amdgcn_s_setprio(0);
;         lsum = xsum32(lsum);
;         const float inv = 1.f / lsum;
;         bf16_t* op = O + (size_t)(row0 + wid * 32 + r) * 1024 + head * 64 + 8 * hh;
;     ...
; #pragma unroll
;         for (int k = 0; k < 2; ++k) {
;             const u32x2 a = AT_PK4(o0, 2 * k), b2 = AT_PK4(o0, 2 * k + 1), c = AT_PK4(o1, 2 * k), d = AT_PK4(o1, 2 * k + 1);
;             const u32x2 s0 = __builtin_amdgcn_permlane32_swap(a[0], b2[0], false, false), s1 = __builtin_amdgcn_permlane32_swap(a[1], b2[1], false, false);
;             const u32x2 t0 = __builtin_amdgcn_permlane32_swap(c[0], d[0], false, false), t1 = __builtin_amdgcn_permlane32_swap(c[1], d[1], false, false);
;             const u32x4 w0 = {s0[0], s1[0], s0[1], s1[1]}, w1 = {t0[0], t1[0], t0[1], t1[1]};
;             *(u32x4*)(op + 16 * k) = w0; *(u32x4*)(op + 32 + 16 * k) = w1;
;         }
.Lamla_noresc_11:
	s_waitcnt lgkmcnt(0)
	s_barrier
	ds_read_b64_tr_b16 v[192:193], v222 offset:3072
	ds_read_b64_tr_b16 v[194:195], v222 offset:4608
	ds_read_b64_tr_b16 v[196:197], v222 offset:3136
	ds_read_b64_tr_b16 v[198:199], v222 offset:4672
	v_mfma_f32_32x32x16_bf16 v[0:15], v[176:179], v[96:99], v[0:15]
	s_mov_b32 s55, s52
	s_mov_b32 s52, s53
	s_mov_b32 s53, s54
	s_mov_b32 s54, s55
	ds_read_b64_tr_b16 v[200:201], v222 offset:9216
	ds_read_b64_tr_b16 v[202:203], v222 offset:10752
	ds_read_b64_tr_b16 v[204:205], v222 offset:9280
	ds_read_b64_tr_b16 v[206:207], v222 offset:10816
	v_mfma_f32_32x32x16_bf16 v[16:31], v[180:183], v[96:99], v[16:31]
	v_mfma_f32_32x32x16_bf16 v[226:241], v[246:249], v[96:99], v[226:241]
	v_mfma_f32_32x32x16_bf16 v[0:15], v[184:187], v[104:107], v[0:15]
	v_mfma_f32_32x32x16_bf16 v[16:31], v[188:191], v[104:107], v[16:31]
	v_mfma_f32_32x32x16_bf16 v[226:241], v[246:249], v[104:107], v[226:241]
	s_waitcnt lgkmcnt(6)
	v_mfma_f32_32x32x16_bf16 v[0:15], v[192:195], v[100:103], v[0:15]
	s_waitcnt lgkmcnt(4)
	v_mfma_f32_32x32x16_bf16 v[16:31], v[196:199], v[100:103], v[16:31]
	v_mfma_f32_32x32x16_bf16 v[226:241], v[246:249], v[100:103], v[226:241]
	s_waitcnt lgkmcnt(2)
	v_mfma_f32_32x32x16_bf16 v[0:15], v[200:203], v[108:111], v[0:15]
	s_waitcnt lgkmcnt(0)
	v_mfma_f32_32x32x16_bf16 v[16:31], v[204:207], v[108:111], v[16:31]
	v_mfma_f32_32x32x16_bf16 v[226:241], v[246:249], v[108:111], v[226:241]
	s_setprio 0
	s_nop 11
	v_div_scale_f32 v208, s[60:61], v226, v226, 1.0
	v_rcp_f32_e32 v209, v208
	s_nop 0
	v_fma_f32 v210, -v208, v209, 1.0
	v_fmac_f32_e32 v209, v210, v209
	v_div_scale_f32 v210, vcc, 1.0, v226, 1.0
	v_mul_f32_e32 v211, v210, v209
	v_fma_f32 v173, -v208, v211, v210
	v_fmac_f32_e32 v211, v173, v209
	v_fma_f32 v208, -v208, v211, v210
	s_nop 1
	v_div_fmas_f32 v208, v208, v209, v211
	v_div_fixup_f32 v166, v208, v226, 1.0
	v_pk_mul_f32 v[0:1], v[0:1], v[166:167] op_sel_hi:[1,0]
	v_pk_mul_f32 v[2:3], v[2:3], v[166:167] op_sel_hi:[1,0]
	v_pk_mul_f32 v[4:5], v[4:5], v[166:167] op_sel_hi:[1,0]
	v_pk_mul_f32 v[6:7], v[6:7], v[166:167] op_sel_hi:[1,0]
	v_pk_mul_f32 v[8:9], v[8:9], v[166:167] op_sel_hi:[1,0]
	v_pk_mul_f32 v[10:11], v[10:11], v[166:167] op_sel_hi:[1,0]
	v_pk_mul_f32 v[12:13], v[12:13], v[166:167] op_sel_hi:[1,0]
	v_pk_mul_f32 v[14:15], v[14:15], v[166:167] op_sel_hi:[1,0]
	v_pk_mul_f32 v[16:17], v[16:17], v[166:167] op_sel_hi:[1,0]
	v_pk_mul_f32 v[18:19], v[18:19], v[166:167] op_sel_hi:[1,0]
	v_pk_mul_f32 v[20:21], v[20:21], v[166:167] op_sel_hi:[1,0]
	v_pk_mul_f32 v[22:23], v[22:23], v[166:167] op_sel_hi:[1,0]
	v_pk_mul_f32 v[24:25], v[24:25], v[166:167] op_sel_hi:[1,0]
	v_pk_mul_f32 v[26:27], v[26:27], v[166:167] op_sel_hi:[1,0]
	v_pk_mul_f32 v[28:29], v[28:29], v[166:167] op_sel_hi:[1,0]
	v_pk_mul_f32 v[30:31], v[30:31], v[166:167] op_sel_hi:[1,0]
	v_cvt_pk_bf16_f32 v96, v0, v1
	v_cvt_pk_bf16_f32 v97, v2, v3
	v_cvt_pk_bf16_f32 v98, v4, v5
	v_cvt_pk_bf16_f32 v99, v6, v7
	v_cvt_pk_bf16_f32 v100, v16, v17
	v_cvt_pk_bf16_f32 v101, v18, v19
	v_cvt_pk_bf16_f32 v102, v20, v21
	v_cvt_pk_bf16_f32 v103, v22, v23
	v_cvt_pk_bf16_f32 v104, v8, v9
	v_cvt_pk_bf16_f32 v105, v10, v11
	v_cvt_pk_bf16_f32 v106, v12, v13
	v_cvt_pk_bf16_f32 v107, v14, v15
	v_cvt_pk_bf16_f32 v108, v24, v25
	v_cvt_pk_bf16_f32 v109, v26, v27
	v_cvt_pk_bf16_f32 v110, v28, v29
	v_cvt_pk_bf16_f32 v111, v30, v31
	s_nop 1
	v_permlane32_swap_b32_e32 v96, v98
	v_permlane32_swap_b32_e32 v97, v99
	v_permlane32_swap_b32_e32 v100, v102
	v_permlane32_swap_b32_e32 v101, v103
	v_permlane32_swap_b32_e32 v104, v106
	v_permlane32_swap_b32_e32 v105, v107
	v_permlane32_swap_b32_e32 v108, v110
	v_permlane32_swap_b32_e32 v109, v111
	global_store_dwordx4 v172, v[96:99], s[16:17]
	global_store_dwordx4 v172, v[100:103], s[16:17] offset:64
	global_store_dwordx4 v172, v[104:107], s[16:17] offset:32
	global_store_dwordx4 v172, v[108:111], s[16:17] offset:96
	s_add_i32 s6, s6, s31
	s_cmp_ge_i32 s6, s8
	s_cbranch_scc0 .Lamla_item

; #define LAS __attribute__((address_space(3)))
; template <bool MLA>
; DI void attn_phase(const int TID, const int BID, LAS unsigned char* lds, const Params& p, bool need_ctx) {
;     constexpr int DK = MLA ? 96 : 64;
;     constexpr int NKS = DK / 16;
;     constexpr int KSTR = (DK + 8) * 2;
;     constexpr int VSTR = 192;
;     constexpr int KBUF = 64 * KSTR, VBUF = 64 * VSTR;
;     constexpr int NKV = MLA ? 16 : 4;
;     constexpr int QS = 16 * DK;
;     const float sc = (MLA ? 0.10206207261596575f : 0.125f) * 1.4426950408889634f;
;     const int tid = TID, wid = tid >> 6, lane = tid & 63, r = lane & 31, hh = lane >> 5;
;     const int n_items = 1024 + (need_ctx ? 128 : 0);
;     bf16_t* O = P_WSB(OFF_H);
;     for (int item = BID; item < n_items; item += gridDim.x) {
;         int b, head, row0, nk;
;         if (item < 1024) {
;             const int rnd = item >> 8, w = item & 255, xcd = w & 7, slot = w >> 3, qb = slot & 7;
;             if (MLA) { const int grp = (rnd * 8 + xcd) * 4 + (slot >> 3); b = grp >> 4; head = grp & 15; }
;             else { const int grp = rnd * 8 + xcd; b = grp >> 2; head = (grp & 3) * 4 + (slot >> 3); }
;             row0 = b * 2048 + qb * 256; nk = NKEY;
;         }
;         else { const int it = item - 1024; b = it >> 4; head = it & 15; row0 = TL + b * 256; nk = 256; }
;         const int kvh = MLA ? head : (head >> 2);
;         const bf16_t* Kb = P_WSB(OFF_K) + (size_t)(b * NKV + kvh) * NKEY * 64;
;         const bf16_t* Vb = P_WSB(OFF_VT) + (size_t)(b * NKV + kvh) * NKEY * 64;
;         const bf16_t* Pb = P_WSB(OFF_KPE) + (size_t)b * NKEY * 32;
;         bf16x8 qf[NKS];
;         {
;             const bf16_t* qp = P_WSB(OFF_Q) + (size_t)(row0 + wid * 32 + r) * QS + head * DK + hh * 8;
; #pragma unroll
;             for (int ks = 0; ks < NKS; ++ks) qf[ks] = *(const bf16x8*)(qp + ks * 16);
;         }
;         u32x4 kreg, vreg; u32x2 preg = {0u, 0u};
.LBB0_318:
	s_andn2_b64 vcc, exec, s[4:5]
	s_cbranch_vccnz .LBB0_339
	s_and_b64 vcc, exec, s[2:3]
	s_cbranch_vccnz .LBB0_339
	v_and_b32_e32 v208, 31, v174
	v_bfe_u32 v209, v174, 5, 1
	v_lshrrev_b32_e32 v210, 6, v174
	v_lshrrev_b32_e32 v211, 3, v174
	v_and_b32_e32 v212, 7, v174
	v_mov_b32_e32 v213, s23
	s_movk_i32 s15, 0x90
	v_mad_u32_u24 v243, v208, s15, v213
	v_lshl_add_u32 v243, v209, 4, v243
	v_mad_u32_u24 v218, v211, s15, v213
	v_lshl_add_u32 v218, v212, 4, v218
	s_movk_i32 s15, 0xc0
	v_bfe_u32 v214, v174, 2, 2
	v_lshl_add_u32 v214, v209, 2, v214
	v_mad_u32_u24 v220, v214, s15, v213
	v_bfe_u32 v215, v174, 4, 1
	v_and_b32_e32 v216, 3, v174
	v_lshlrev_b32_e32 v215, 5, v215
	v_lshl_add_u32 v215, v216, 3, v215
	v_add_u32_e32 v220, v220, v215
	v_add_u32_e32 v220, 0x4800, v220
	v_mad_u32_u24 v221, v211, s15, v213
	v_lshl_add_u32 v221, v212, 4, v221
	v_add_u32_e32 v221, 0x4800, v221
	v_lshlrev_b32_e32 v225, 7, v211
	v_lshl_add_u32 v225, v212, 4, v225
	v_lshl_add_u32 v217, v210, 5, v208
	s_movk_i32 s15, 0x800
	v_mul_u32_u24_e32 v171, s15, v217
	v_lshl_add_u32 v171, v209, 4, v171
	v_lshlrev_b32_e32 v172, 11, v217
	v_lshl_add_u32 v172, v209, 4, v172
	v_mov_b32_e32 v167, 0
	v_mov_b32_e32 v246, 0x3f803f80
	v_mov_b32_e32 v247, 0x3f803f80
	v_mov_b32_e32 v248, 0x3f803f80
	v_mov_b32_e32 v249, 0x3f803f80
	v_readfirstlane_b32 s58, v210
	s_mov_b32 s6, s83
	s_lshr_b32 s58, s58, 2

; #define AT_GLOADK(k0) do { kreg = *(const u32x4*)(Kb + (size_t)((k0) + (tid >> 3)) * 64 + (tid & 7) * 8); \
;             if (MLA) preg = *(const u32x2*)(Pb + (size_t)((k0) + (tid >> 3)) * 32 + (tid & 7) * 4); } while (0)
; #define AT_GLOADV(k0) do { vreg = *(const u32x4*)(Vb + (size_t)((k0) + (tid >> 3)) * 64 + (tid & 7) * 8); } while (0)
; #define AT_WRITEK(buf) do { *(LAS u32x4*)(lds + (buf) * KBUF + (tid >> 3) * KSTR + (tid & 7) * 16) = kreg; \
;             if (MLA) *(LAS u32x2*)(lds + (buf) * KBUF + (tid >> 3) * KSTR + 128 + (tid & 7) * 8) = preg; } while (0)
; #define AT_WRITEV(buf) do { *(LAS u32x4*)(lds + 2 * KBUF + (buf) * VBUF + (tid >> 3) * VSTR + (tid & 7) * 16) = vreg; } while (0)
; template <bool MLA>
; DI void attn_phase(const int TID, const int BID, LAS unsigned char* lds, const Params& p, bool need_ctx) {
;     ...
;         const bf16_t* Kb = P_WSB(OFF_K) + (size_t)(b * NKV + kvh) * NKEY * 64;
;         const bf16_t* Vb = P_WSB(OFF_VT) + (size_t)(b * NKV + kvh) * NKEY * 64;
;         const bf16_t* Pb = P_WSB(OFF_KPE) + (size_t)b * NKEY * 32;
;         bf16x8 qf[NKS];
;         {
;             const bf16_t* qp = P_WSB(OFF_Q) + (size_t)(row0 + wid * 32 + r) * QS + head * DK + hh * 8;
; #pragma unroll
;             for (int ks = 0; ks < NKS; ++ks) qf[ks] = *(const bf16x8*)(qp + ks * 16);
;         }
;         u32x4 kreg, vreg; u32x2 preg = {0u, 0u};
;     ...
;         f32x16 o0, o1, sa0, sa1, sb0, sb1;
; #pragma unroll
;         for (int j = 0; j < 16; ++j) { o0[j] = 0.f; o1[j] = 0.f; }
;         float mrun = -1e30f, lsum = 0.f;
;         if (wid >= 4) __builtin_amdgcn_s_setprio(1);
;         const int ntile = nk >> 6;
;         AT_GLOADK(0); AT_GLOADV(0); AT_WRITEK(0); AT_WRITEV(0);
;         AT_GLOADK(64); AT_WRITEK(1);
;         __syncthreads();
;         AT_QK(sa0, sa1, 0);
;         __syncthreads();
.Lagqa_decoded:
	s_lshr_b32 s19, s18, 2
	s_lshl_b32 s21, s15, 2
	s_add_i32 s21, s21, s19
	s_mul_i32 s21, s21, 0x48000
	s_add_u32 s2, s26, s21
	s_addc_u32 s3, s27, 0
	v_readlane_b32 s60, v254, 36
	v_readlane_b32 s61, v254, 37
	s_add_u32 s4, s60, s21
	s_addc_u32 s5, s61, 0
	v_readlane_b32 s60, v254, 27
	v_readlane_b32 s61, v254, 28
	s_mul_i32 s21, s20, 0x800
	s_mul_i32 s55, s18, 0x80
	s_add_i32 s21, s21, s55
	s_add_u32 s12, s60, s21
	s_addc_u32 s13, s61, 0
	v_readlane_b32 s60, v254, 34
	v_readlane_b32 s61, v254, 35
	s_lshl_b32 s21, s20, 11
	s_lshl_b32 s55, s18, 7
	s_add_i32 s21, s21, s55
	s_add_u32 s16, s60, s21
	s_addc_u32 s17, s61, 0
	global_load_dwordx4 v[112:115], v171, s[12:13]
	global_load_dwordx4 v[116:119], v171, s[12:13] offset:32
	global_load_dwordx4 v[120:123], v171, s[12:13] offset:64
	global_load_dwordx4 v[124:127], v171, s[12:13] offset:96
	global_load_dwordx4 v[136:139], v225, s[2:3]
	s_add_u32 s2, s2, 0x2000
	s_addc_u32 s3, s3, 0
	global_load_dwordx4 v[140:143], v225, s[2:3]
	s_add_u32 s2, s2, 0x2000
	s_addc_u32 s3, s3, 0
	global_load_dwordx4 v[144:147], v225, s[4:5]
	s_add_u32 s4, s4, 0x2000
	s_addc_u32 s5, s5, 0
	global_load_dwordx4 v[152:155], v225, s[2:3]
	s_add_u32 s2, s2, 0x2000
	s_addc_u32 s3, s3, 0
	global_load_dwordx4 v[156:159], v225, s[4:5]
	s_add_u32 s4, s4, 0x2000
	s_addc_u32 s5, s5, 0
	s_mov_b32 s52, 0x3000
	s_mov_b32 s53, 0x6000
	s_mov_b32 s54, 0
	v_mov_b64_e32 v[0:1], 0
	v_mov_b64_e32 v[2:3], 0
	v_mov_b64_e32 v[4:5], 0
	v_mov_b64_e32 v[6:7], 0
	v_mov_b64_e32 v[8:9], 0
	v_mov_b64_e32 v[10:11], 0
	v_mov_b64_e32 v[12:13], 0
	v_mov_b64_e32 v[14:15], 0
	v_mov_b64_e32 v[16:17], 0
	v_mov_b64_e32 v[18:19], 0
	v_mov_b64_e32 v[20:21], 0
	v_mov_b64_e32 v[22:23], 0
	v_mov_b64_e32 v[24:25], 0
	v_mov_b64_e32 v[26:27], 0
	v_mov_b64_e32 v[28:29], 0
	v_mov_b64_e32 v[30:31], 0
	v_mov_b32_e32 v162, 0xf149f2ca
	v_mov_b32_e32 v164, 0xf149f2ca
	v_mov_b32_e32 v163, 0x7149f2ca
	v_mov_b64_e32 v[226:227], 0
	v_mov_b64_e32 v[228:229], 0
	v_mov_b64_e32 v[230:231], 0
	v_mov_b64_e32 v[232:233], 0
	v_mov_b64_e32 v[234:235], 0
	v_mov_b64_e32 v[236:237], 0
	v_mov_b64_e32 v[238:239], 0
	v_mov_b64_e32 v[240:241], 0
	s_barrier
	s_waitcnt vmcnt(4)
	ds_write_b128 v218, v[136:139]
	s_waitcnt vmcnt(3)
	ds_write_b128 v218, v[140:143] offset:9216
	s_waitcnt vmcnt(2)
	ds_write_b128 v221, v[144:147]
	s_waitcnt lgkmcnt(0)
	s_barrier
	s_cmp_eq_u32 s58, 0
	s_cbranch_scc1 .Lagqa_prio
	s_setprio 1
.Lagqa_prio:
	ds_read_b128 v[136:139], v243 offset:0
	ds_read_b128 v[140:143], v243 offset:4608
	ds_read_b128 v[144:147], v243 offset:32
	ds_read_b128 v[148:151], v243 offset:4640
	s_waitcnt lgkmcnt(3)
	v_mfma_f32_32x32x16_bf16 v[32:47], v[136:139], v[112:115], 0
	ds_read_b128 v[136:139], v243 offset:64
	s_waitcnt lgkmcnt(3)
	v_mfma_f32_32x32x16_bf16 v[48:63], v[140:143], v[112:115], 0
	ds_read_b128 v[140:143], v243 offset:4672
	s_waitcnt lgkmcnt(3)
	v_mfma_f32_32x32x16_bf16 v[32:47], v[144:147], v[116:119], v[32:47]
	ds_read_b128 v[144:147], v243 offset:96
	s_waitcnt lgkmcnt(3)
	v_mfma_f32_32x32x16_bf16 v[48:63], v[148:151], v[116:119], v[48:63]
	ds_read_b128 v[148:151], v243 offset:4704
	s_waitcnt lgkmcnt(3)
	v_mfma_f32_32x32x16_bf16 v[32:47], v[136:139], v[120:123], v[32:47]
	s_waitcnt lgkmcnt(2)
	v_mfma_f32_32x32x16_bf16 v[48:63], v[140:143], v[120:123], v[48:63]
	s_waitcnt lgkmcnt(1)
	v_mfma_f32_32x32x16_bf16 v[32:47], v[144:147], v[124:127], v[32:47]
	s_waitcnt lgkmcnt(0)
	v_mfma_f32_32x32x16_bf16 v[48:63], v[148:151], v[124:127], v[48:63]
	s_waitcnt lgkmcnt(0)
	s_nop 7
	s_barrier
	ds_read_b128 v[136:139], v243 offset:9216
	ds_read_b128 v[140:143], v243 offset:13824
	ds_read_b128 v[144:147], v243 offset:9248
	ds_read_b128 v[148:151], v243 offset:13856
	s_waitcnt lgkmcnt(3)
	v_mfma_f32_32x32x16_bf16 v[64:79], v[136:139], v[112:115], 0
	v_max3_f32 v168, v32, v33, v34
	v_max3_f32 v170, v48, v49, v50
	v_max3_f32 v168, v168, v35, v36
	v_max3_f32 v170, v170, v51, v52
	v_max3_f32 v168, v168, v37, v38
	v_max3_f32 v170, v170, v53, v54
	v_max3_f32 v168, v168, v39, v40
	v_max3_f32 v170, v170, v55, v56
	v_max3_f32 v168, v168, v41, v42
	v_max3_f32 v170, v170, v57, v58
	v_max3_f32 v168, v168, v43, v44
	v_max3_f32 v170, v170, v59, v60
	v_max3_f32 v168, v168, v45, v46
	v_max3_f32 v170, v170, v61, v62
	v_max_f32_e32 v168, v168, v47
	v_max_f32_e32 v170, v170, v63
	v_max_f32_e32 v168, v168, v170
	ds_read_b128 v[136:139], v243 offset:9280
	s_mov_b32 s55, s52
	s_mov_b32 s52, s53
	s_mov_b32 s53, s54
	s_mov_b32 s54, s55
	s_mov_b32 s9, 0
	s_waitcnt lgkmcnt(3)
	v_mfma_f32_32x32x16_bf16 v[80:95], v[140:143], v[112:115], 0
	v_mov_b32_e32 v170, v168
	s_nop 1
	v_permlane32_swap_b32_e32 v168, v170
	v_max_f32_e32 v168, v168, v170
	v_mul_f32_e32 v168, 0x3e38aa3b, v168
	v_cmp_gt_f32_e32 vcc, v168, v164
	s_cbranch_vccz .Lagqa_nors_1
	v_max_f32_e32 v170, v162, v168
	v_sub_f32_e32 v166, v162, v170
	v_exp_f32_e32 v166, v166
	v_mov_b32_e32 v162, v170
	v_add_f32_e32 v164, 0x41000000, v170
	v_xor_b32_e32 v163, 0x80000000, v170
	s_mov_b32 s9, 1
.Lagqa_nors_1:
	v_fmamk_f32 v32, v32, 0x3e38aa3b, v163
	v_fmamk_f32 v48, v48, 0x3e38aa3b, v163
	v_exp_f32_e32 v32, v32
	v_exp_f32_e32 v48, v48
	v_fmamk_f32 v33, v33, 0x3e38aa3b, v163
	v_fmamk_f32 v49, v49, 0x3e38aa3b, v163
	v_exp_f32_e32 v33, v33
	v_exp_f32_e32 v49, v49
	ds_read_b128 v[140:143], v243 offset:13888
	global_load_dwordx4 v[208:211], v225, s[2:3]
	global_load_dwordx4 v[212:215], v225, s[4:5]
	s_add_u32 s2, s2, 0x2000
	s_addc_u32 s3, s3, 0
	s_add_u32 s4, s4, 0x2000
	s_addc_u32 s5, s5, 0
	v_add_u32_e32 v223, s53, v220
	v_add_u32_e32 v224, s54, v221
	s_waitcnt lgkmcnt(3)
	v_mfma_f32_32x32x16_bf16 v[64:79], v[144:147], v[116:119], v[64:79]
	v_fmamk_f32 v34, v34, 0x3e38aa3b, v163
	v_fmamk_f32 v50, v50, 0x3e38aa3b, v163
	v_exp_f32_e32 v34, v34
	v_exp_f32_e32 v50, v50
	v_cvt_pk_bf16_f32 v96, v32, v33
	v_cvt_pk_bf16_f32 v104, v48, v49
	v_fmamk_f32 v35, v35, 0x3e38aa3b, v163
	v_fmamk_f32 v51, v51, 0x3e38aa3b, v163
	v_exp_f32_e32 v35, v35
	v_exp_f32_e32 v51, v51
	v_fmamk_f32 v36, v36, 0x3e38aa3b, v163
	v_fmamk_f32 v52, v52, 0x3e38aa3b, v163
	ds_read_b128 v[144:147], v243 offset:9312
	ds_read_b64_tr_b16 v[176:177], v223 offset:0
	ds_read_b64_tr_b16 v[178:179], v223 offset:1536
	s_waitcnt lgkmcnt(5)
	v_mfma_f32_32x32x16_bf16 v[80:95], v[148:151], v[116:119], v[80:95]
	v_exp_f32_e32 v36, v36
	v_exp_f32_e32 v52, v52
	v_cvt_pk_bf16_f32 v97, v34, v35
	v_cvt_pk_bf16_f32 v105, v50, v51
	v_fmamk_f32 v37, v37, 0x3e38aa3b, v163
	v_fmamk_f32 v53, v53, 0x3e38aa3b, v163
	v_exp_f32_e32 v37, v37
	v_exp_f32_e32 v53, v53
	v_fmamk_f32 v38, v38, 0x3e38aa3b, v163
	v_fmamk_f32 v54, v54, 0x3e38aa3b, v163
	v_exp_f32_e32 v38, v38
	v_exp_f32_e32 v54, v54
	ds_read_b128 v[148:151], v243 offset:13920
	ds_read_b64_tr_b16 v[180:181], v223 offset:64
	ds_read_b64_tr_b16 v[182:183], v223 offset:1600
	s_waitcnt lgkmcnt(7)
	v_mfma_f32_32x32x16_bf16 v[64:79], v[136:139], v[120:123], v[64:79]
	v_cvt_pk_bf16_f32 v98, v36, v37
	v_cvt_pk_bf16_f32 v106, v52, v53
	v_fmamk_f32 v39, v39, 0x3e38aa3b, v163
	v_fmamk_f32 v55, v55, 0x3e38aa3b, v163
	v_exp_f32_e32 v39, v39
	v_exp_f32_e32 v55, v55
	v_fmamk_f32 v40, v40, 0x3e38aa3b, v163
	v_fmamk_f32 v56, v56, 0x3e38aa3b, v163
	v_exp_f32_e32 v40, v40
	v_exp_f32_e32 v56, v56
	v_cvt_pk_bf16_f32 v99, v38, v39
	v_cvt_pk_bf16_f32 v107, v54, v55
	ds_read_b64_tr_b16 v[184:185], v223 offset:6144
	ds_read_b64_tr_b16 v[186:187], v223 offset:7680
	s_waitcnt vmcnt(3)
	ds_write_b128 v218, v[152:155]
	s_waitcnt vmcnt(2)
	ds_write_b128 v224, v[156:159]
	s_waitcnt lgkmcnt(10)
	v_mfma_f32_32x32x16_bf16 v[80:95], v[140:143], v[120:123], v[80:95]
	v_fmamk_f32 v41, v41, 0x3e38aa3b, v163
	v_fmamk_f32 v57, v57, 0x3e38aa3b, v163
	v_exp_f32_e32 v41, v41
	v_exp_f32_e32 v57, v57
	v_fmamk_f32 v42, v42, 0x3e38aa3b, v163
	v_fmamk_f32 v58, v58, 0x3e38aa3b, v163
	v_exp_f32_e32 v42, v42
	v_exp_f32_e32 v58, v58
	v_cvt_pk_bf16_f32 v100, v40, v41
	v_cvt_pk_bf16_f32 v108, v56, v57
	v_fmamk_f32 v43, v43, 0x3e38aa3b, v163
	v_fmamk_f32 v59, v59, 0x3e38aa3b, v163
	v_exp_f32_e32 v43, v43
	ds_read_b64_tr_b16 v[188:189], v223 offset:6208
	ds_read_b64_tr_b16 v[190:191], v223 offset:7744
	s_waitcnt lgkmcnt(11)
	v_mfma_f32_32x32x16_bf16 v[64:79], v[144:147], v[124:127], v[64:79]
	v_exp_f32_e32 v59, v59
	v_fmamk_f32 v44, v44, 0x3e38aa3b, v163
	v_fmamk_f32 v60, v60, 0x3e38aa3b, v163
	v_exp_f32_e32 v44, v44
	v_exp_f32_e32 v60, v60
	v_cvt_pk_bf16_f32 v101, v42, v43
	v_cvt_pk_bf16_f32 v109, v58, v59
	v_fmamk_f32 v45, v45, 0x3e38aa3b, v163
	v_fmamk_f32 v61, v61, 0x3e38aa3b, v163
	v_exp_f32_e32 v45, v45
	v_exp_f32_e32 v61, v61
	s_waitcnt lgkmcnt(8)
	v_mfma_f32_32x32x16_bf16 v[80:95], v[148:151], v[124:127], v[80:95]
	v_fmamk_f32 v46, v46, 0x3e38aa3b, v163
	v_fmamk_f32 v62, v62, 0x3e38aa3b, v163
	v_exp_f32_e32 v46, v46
	v_exp_f32_e32 v62, v62
	v_cvt_pk_bf16_f32 v102, v44, v45
	v_cvt_pk_bf16_f32 v110, v60, v61
	v_fmamk_f32 v47, v47, 0x3e38aa3b, v163
	v_fmamk_f32 v63, v63, 0x3e38aa3b, v163
	v_exp_f32_e32 v47, v47
	v_exp_f32_e32 v63, v63
	v_cvt_pk_bf16_f32 v103, v46, v47
	v_cvt_pk_bf16_f32 v111, v62, v63
	s_waitcnt lgkmcnt(0)
	s_barrier
	s_cmp_eq_u32 s7, 0
	s_cbranch_scc1 .Lagqa_tail
.Lagqa_loop:
	ds_read_b128 v[136:139], v243 offset:0
	ds_read_b128 v[140:143], v243 offset:4608
	ds_read_b128 v[144:147], v243 offset:32
	ds_read_b128 v[148:151], v243 offset:4640
	v_mfma_f32_32x32x16_bf16 v[0:15], v[176:179], v[96:99], v[0:15]
	v_max3_f32 v168, v64, v65, v66
	v_max3_f32 v170, v80, v81, v82
	v_max3_f32 v168, v168, v67, v68
	v_max3_f32 v170, v170, v83, v84
	v_max3_f32 v168, v168, v69, v70
	v_max3_f32 v170, v170, v85, v86
	v_max3_f32 v168, v168, v71, v72
	s_mov_b32 s55, s52
	s_mov_b32 s52, s53
	s_mov_b32 s53, s54
	s_mov_b32 s54, s55
	s_mov_b32 s9, 0
	v_mfma_f32_32x32x16_bf16 v[16:31], v[180:183], v[96:99], v[16:31]
	v_max3_f32 v170, v170, v87, v88
	v_max3_f32 v168, v168, v73, v74
	v_max3_f32 v170, v170, v89, v90
	v_max3_f32 v168, v168, v75, v76
	v_max3_f32 v170, v170, v91, v92
	v_max3_f32 v168, v168, v77, v78
	v_max3_f32 v170, v170, v93, v94
	global_load_dwordx4 v[152:155], v225, s[2:3]
	global_load_dwordx4 v[156:159], v225, s[4:5]
	s_add_u32 s2, s2, 0x2000
	s_addc_u32 s3, s3, 0
	s_add_u32 s4, s4, 0x2000
	s_addc_u32 s5, s5, 0
	v_add_u32_e32 v222, s53, v220
	v_add_u32_e32 v224, s54, v221
	v_mfma_f32_32x32x16_bf16 v[226:241], v[246:249], v[96:99], v[226:241]
	v_max_f32_e32 v168, v168, v79
	v_max_f32_e32 v170, v170, v95
	v_max_f32_e32 v168, v168, v170
	v_mov_b32_e32 v170, v168
	s_nop 1
	v_permlane32_swap_b32_e32 v168, v170
	v_max_f32_e32 v168, v168, v170
	v_mul_f32_e32 v168, 0x3e38aa3b, v168
	v_mfma_f32_32x32x16_bf16 v[0:15], v[184:187], v[104:107], v[0:15]
	v_cmp_gt_f32_e32 vcc, v168, v164
	s_cbranch_vccz .Lagqa_nors_2
	v_max_f32_e32 v170, v162, v168
	v_sub_f32_e32 v166, v162, v170
	v_exp_f32_e32 v166, v166
	v_mov_b32_e32 v162, v170
	v_add_f32_e32 v164, 0x41000000, v170
	v_xor_b32_e32 v163, 0x80000000, v170
	s_mov_b32 s9, 1
.Lagqa_nors_2:
	v_fmamk_f32 v64, v64, 0x3e38aa3b, v163
	v_fmamk_f32 v80, v80, 0x3e38aa3b, v163
	v_exp_f32_e32 v64, v64
	ds_read_b64_tr_b16 v[192:193], v223 offset:3072
	ds_read_b64_tr_b16 v[194:195], v223 offset:4608
	v_mfma_f32_32x32x16_bf16 v[16:31], v[188:191], v[104:107], v[16:31]
	v_exp_f32_e32 v80, v80
	v_fmamk_f32 v65, v65, 0x3e38aa3b, v163
	v_fmamk_f32 v81, v81, 0x3e38aa3b, v163
	v_exp_f32_e32 v65, v65
	v_exp_f32_e32 v81, v81
	ds_read_b64_tr_b16 v[196:197], v223 offset:3136
	ds_read_b64_tr_b16 v[198:199], v223 offset:4672
	v_mfma_f32_32x32x16_bf16 v[226:241], v[246:249], v[104:107], v[226:241]
	v_fmamk_f32 v66, v66, 0x3e38aa3b, v163
	v_fmamk_f32 v82, v82, 0x3e38aa3b, v163
	v_exp_f32_e32 v66, v66
	v_exp_f32_e32 v82, v82
	ds_read_b64_tr_b16 v[200:201], v223 offset:9216
	ds_read_b64_tr_b16 v[202:203], v223 offset:10752
	s_waitcnt lgkmcnt(9)
	v_mfma_f32_32x32x16_bf16 v[32:47], v[136:139], v[112:115], 0
	v_cvt_pk_bf16_f32 v96, v64, v65
	v_cvt_pk_bf16_f32 v104, v80, v81
	v_fmamk_f32 v67, v67, 0x3e38aa3b, v163
	v_fmamk_f32 v83, v83, 0x3e38aa3b, v163
	v_exp_f32_e32 v67, v67
	v_exp_f32_e32 v83, v83
	ds_read_b128 v[136:139], v243 offset:64
	ds_read_b64_tr_b16 v[204:205], v223 offset:9280
	ds_read_b64_tr_b16 v[206:207], v223 offset:10816
	s_waitcnt lgkmcnt(11)
	v_mfma_f32_32x32x16_bf16 v[48:63], v[140:143], v[112:115], 0
	v_fmamk_f32 v68, v68, 0x3e38aa3b, v163
	v_fmamk_f32 v84, v84, 0x3e38aa3b, v163
	v_exp_f32_e32 v68, v68
	v_exp_f32_e32 v84, v84
	ds_read_b128 v[140:143], v243 offset:4672
	s_waitcnt lgkmcnt(11)
	v_mfma_f32_32x32x16_bf16 v[32:47], v[144:147], v[116:119], v[32:47]
	v_cvt_pk_bf16_f32 v97, v66, v67
	v_cvt_pk_bf16_f32 v105, v82, v83
	v_fmamk_f32 v69, v69, 0x3e38aa3b, v163
	v_fmamk_f32 v85, v85, 0x3e38aa3b, v163
	v_exp_f32_e32 v69, v69
	ds_read_b128 v[144:147], v243 offset:96
	s_waitcnt lgkmcnt(11)
	v_mfma_f32_32x32x16_bf16 v[48:63], v[148:151], v[116:119], v[48:63]
	v_exp_f32_e32 v85, v85
	v_fmamk_f32 v70, v70, 0x3e38aa3b, v163
	v_fmamk_f32 v86, v86, 0x3e38aa3b, v163
	v_exp_f32_e32 v70, v70
	v_exp_f32_e32 v86, v86
	ds_read_b128 v[148:151], v243 offset:4704
	s_waitcnt lgkmcnt(5)
	v_mfma_f32_32x32x16_bf16 v[32:47], v[136:139], v[120:123], v[32:47]
	v_cvt_pk_bf16_f32 v98, v68, v69
	v_cvt_pk_bf16_f32 v106, v84, v85
	v_fmamk_f32 v71, v71, 0x3e38aa3b, v163
	v_fmamk_f32 v87, v87, 0x3e38aa3b, v163
	v_exp_f32_e32 v71, v71
	s_waitcnt lgkmcnt(2)
	v_mfma_f32_32x32x16_bf16 v[48:63], v[140:143], v[120:123], v[48:63]
	v_exp_f32_e32 v87, v87
	v_fmamk_f32 v72, v72, 0x3e38aa3b, v163
	v_fmamk_f32 v88, v88, 0x3e38aa3b, v163
	v_exp_f32_e32 v72, v72
	s_waitcnt vmcnt(3)
	ds_write_b128 v218, v[208:211] offset:9216
	s_waitcnt vmcnt(2)
	ds_write_b128 v224, v[212:215]
	s_waitcnt lgkmcnt(3)
	v_mfma_f32_32x32x16_bf16 v[32:47], v[144:147], v[124:127], v[32:47]
	v_exp_f32_e32 v88, v88
	v_cvt_pk_bf16_f32 v99, v70, v71
	v_cvt_pk_bf16_f32 v107, v86, v87
	v_fmamk_f32 v73, v73, 0x3e38aa3b, v163
	v_fmamk_f32 v89, v89, 0x3e38aa3b, v163
	v_exp_f32_e32 v73, v73
	s_waitcnt lgkmcnt(2)
	v_mfma_f32_32x32x16_bf16 v[48:63], v[148:151], v[124:127], v[48:63]
	v_exp_f32_e32 v89, v89
	v_fmamk_f32 v74, v74, 0x3e38aa3b, v163
	v_fmamk_f32 v90, v90, 0x3e38aa3b, v163
	v_exp_f32_e32 v74, v74
	v_mfma_f32_32x32x16_bf16 v[0:15], v[192:195], v[100:103], v[0:15]
	v_exp_f32_e32 v90, v90
	v_fmamk_f32 v75, v75, 0x3e38aa3b, v163
	v_fmamk_f32 v91, v91, 0x3e38aa3b, v163
	v_exp_f32_e32 v75, v75
	v_exp_f32_e32 v91, v91
	ds_read_b64_tr_b16 v[176:177], v222 offset:0
	ds_read_b64_tr_b16 v[178:179], v222 offset:1536
	v_mfma_f32_32x32x16_bf16 v[16:31], v[196:199], v[100:103], v[16:31]
	v_fmamk_f32 v76, v76, 0x3e38aa3b, v163
	v_fmamk_f32 v92, v92, 0x3e38aa3b, v163
	v_exp_f32_e32 v76, v76
	v_exp_f32_e32 v92, v92
	ds_read_b64_tr_b16 v[180:181], v222 offset:64
	ds_read_b64_tr_b16 v[182:183], v222 offset:1600
	v_mfma_f32_32x32x16_bf16 v[226:241], v[246:249], v[100:103], v[226:241]
	v_cvt_pk_bf16_f32 v100, v72, v73
	v_cvt_pk_bf16_f32 v101, v74, v75
	v_fmamk_f32 v77, v77, 0x3e38aa3b, v163
	v_fmamk_f32 v93, v93, 0x3e38aa3b, v163
	v_exp_f32_e32 v77, v77
	v_exp_f32_e32 v93, v93
	ds_read_b64_tr_b16 v[184:185], v222 offset:6144
	ds_read_b64_tr_b16 v[186:187], v222 offset:7680
	v_mfma_f32_32x32x16_bf16 v[0:15], v[200:203], v[108:111], v[0:15]
	v_fmamk_f32 v78, v78, 0x3e38aa3b, v163
	v_fmamk_f32 v94, v94, 0x3e38aa3b, v163
	v_exp_f32_e32 v78, v78
	v_exp_f32_e32 v94, v94
	ds_read_b64_tr_b16 v[188:189], v222 offset:6208
	ds_read_b64_tr_b16 v[190:191], v222 offset:7744
	v_mfma_f32_32x32x16_bf16 v[16:31], v[204:207], v[108:111], v[16:31]
	v_cvt_pk_bf16_f32 v102, v76, v77
	v_fmamk_f32 v79, v79, 0x3e38aa3b, v163
	v_fmamk_f32 v95, v95, 0x3e38aa3b, v163
	v_exp_f32_e32 v79, v79
	v_exp_f32_e32 v95, v95
	v_mfma_f32_32x32x16_bf16 v[226:241], v[246:249], v[108:111], v[226:241]
	v_cvt_pk_bf16_f32 v108, v88, v89
	v_cvt_pk_bf16_f32 v109, v90, v91
	v_cvt_pk_bf16_f32 v110, v92, v93
	v_cvt_pk_bf16_f32 v103, v78, v79
	v_cvt_pk_bf16_f32 v111, v94, v95
	s_cmp_lg_u32 s9, 0
	s_cbranch_scc0 .Lagqa_noresc_3
	s_nop 15
	v_pk_mul_f32 v[0:1], v[0:1], v[166:167] op_sel_hi:[1,0]
	v_pk_mul_f32 v[2:3], v[2:3], v[166:167] op_sel_hi:[1,0]
	v_pk_mul_f32 v[4:5], v[4:5], v[166:167] op_sel_hi:[1,0]
	v_pk_mul_f32 v[6:7], v[6:7], v[166:167] op_sel_hi:[1,0]
	v_pk_mul_f32 v[8:9], v[8:9], v[166:167] op_sel_hi:[1,0]
	v_pk_mul_f32 v[10:11], v[10:11], v[166:167] op_sel_hi:[1,0]
	v_pk_mul_f32 v[12:13], v[12:13], v[166:167] op_sel_hi:[1,0]
	v_pk_mul_f32 v[14:15], v[14:15], v[166:167] op_sel_hi:[1,0]
	v_pk_mul_f32 v[16:17], v[16:17], v[166:167] op_sel_hi:[1,0]
	v_pk_mul_f32 v[18:19], v[18:19], v[166:167] op_sel_hi:[1,0]
	v_pk_mul_f32 v[20:21], v[20:21], v[166:167] op_sel_hi:[1,0]
	v_pk_mul_f32 v[22:23], v[22:23], v[166:167] op_sel_hi:[1,0]
	v_pk_mul_f32 v[24:25], v[24:25], v[166:167] op_sel_hi:[1,0]
	v_pk_mul_f32 v[26:27], v[26:27], v[166:167] op_sel_hi:[1,0]
	v_pk_mul_f32 v[28:29], v[28:29], v[166:167] op_sel_hi:[1,0]
	v_pk_mul_f32 v[30:31], v[30:31], v[166:167] op_sel_hi:[1,0]
	v_mul_f32_e32 v226, v226, v166
.Lagqa_noresc_3:
	s_waitcnt lgkmcnt(0)
	s_barrier
	ds_read_b128 v[136:139], v243 offset:9216
	ds_read_b128 v[140:143], v243 offset:13824
	ds_read_b128 v[144:147], v243 offset:9248
	ds_read_b128 v[148:151], v243 offset:13856
	v_mfma_f32_32x32x16_bf16 v[0:15], v[176:179], v[96:99], v[0:15]
	v_max3_f32 v168, v32, v33, v34
	v_max3_f32 v170, v48, v49, v50
	v_max3_f32 v168, v168, v35, v36
	v_max3_f32 v170, v170, v51, v52
	v_max3_f32 v168, v168, v37, v38
	v_max3_f32 v170, v170, v53, v54
	v_max3_f32 v168, v168, v39, v40
	s_mov_b32 s55, s52
	s_mov_b32 s52, s53
	s_mov_b32 s53, s54
	s_mov_b32 s54, s55
	s_mov_b32 s9, 0
	v_mfma_f32_32x32x16_bf16 v[16:31], v[180:183], v[96:99], v[16:31]
	v_max3_f32 v170, v170, v55, v56
	v_max3_f32 v168, v168, v41, v42
	v_max3_f32 v170, v170, v57, v58
	v_max3_f32 v168, v168, v43, v44
	v_max3_f32 v170, v170, v59, v60
	v_max3_f32 v168, v168, v45, v46
	v_max3_f32 v170, v170, v61, v62
	global_load_dwordx4 v[208:211], v225, s[2:3]
	global_load_dwordx4 v[212:215], v225, s[4:5]
	s_add_u32 s2, s2, 0x2000
	s_addc_u32 s3, s3, 0
	s_add_u32 s4, s4, 0x2000
	s_addc_u32 s5, s5, 0
	v_add_u32_e32 v223, s53, v220
	v_add_u32_e32 v224, s54, v221
	v_mfma_f32_32x32x16_bf16 v[226:241], v[246:249], v[96:99], v[226:241]
	v_max_f32_e32 v168, v168, v47
	v_max_f32_e32 v170, v170, v63
	v_max_f32_e32 v168, v168, v170
	v_mov_b32_e32 v170, v168
	s_nop 1
	v_permlane32_swap_b32_e32 v168, v170
	v_max_f32_e32 v168, v168, v170
	v_mul_f32_e32 v168, 0x3e38aa3b, v168
	v_mfma_f32_32x32x16_bf16 v[0:15], v[184:187], v[104:107], v[0:15]
	v_cmp_gt_f32_e32 vcc, v168, v164
	s_cbranch_vccz .Lagqa_nors_4
	v_max_f32_e32 v170, v162, v168
	v_sub_f32_e32 v166, v162, v170
	v_exp_f32_e32 v166, v166
	v_mov_b32_e32 v162, v170
	v_add_f32_e32 v164, 0x41000000, v170
	v_xor_b32_e32 v163, 0x80000000, v170
	s_mov_b32 s9, 1
.Lagqa_nors_4:
	v_fmamk_f32 v32, v32, 0x3e38aa3b, v163
	v_fmamk_f32 v48, v48, 0x3e38aa3b, v163
	v_exp_f32_e32 v32, v32
	ds_read_b64_tr_b16 v[192:193], v222 offset:3072
	ds_read_b64_tr_b16 v[194:195], v222 offset:4608
	v_mfma_f32_32x32x16_bf16 v[16:31], v[188:191], v[104:107], v[16:31]
	v_exp_f32_e32 v48, v48
	v_fmamk_f32 v33, v33, 0x3e38aa3b, v163
	v_fmamk_f32 v49, v49, 0x3e38aa3b, v163
	v_exp_f32_e32 v33, v33
	v_exp_f32_e32 v49, v49
	ds_read_b64_tr_b16 v[196:197], v222 offset:3136
	ds_read_b64_tr_b16 v[198:199], v222 offset:4672
	v_mfma_f32_32x32x16_bf16 v[226:241], v[246:249], v[104:107], v[226:241]
	v_fmamk_f32 v34, v34, 0x3e38aa3b, v163
	v_fmamk_f32 v50, v50, 0x3e38aa3b, v163
	v_exp_f32_e32 v34, v34
	v_exp_f32_e32 v50, v50
	ds_read_b64_tr_b16 v[200:201], v222 offset:9216
	ds_read_b64_tr_b16 v[202:203], v222 offset:10752
	s_waitcnt lgkmcnt(9)
	v_mfma_f32_32x32x16_bf16 v[64:79], v[136:139], v[112:115], 0
	v_cvt_pk_bf16_f32 v96, v32, v33
	v_cvt_pk_bf16_f32 v104, v48, v49
	v_fmamk_f32 v35, v35, 0x3e38aa3b, v163
	v_fmamk_f32 v51, v51, 0x3e38aa3b, v163
	v_exp_f32_e32 v35, v35
	v_exp_f32_e32 v51, v51
	ds_read_b128 v[136:139], v243 offset:9280
	ds_read_b64_tr_b16 v[204:205], v222 offset:9280
	ds_read_b64_tr_b16 v[206:207], v222 offset:10816
	s_waitcnt lgkmcnt(11)
	v_mfma_f32_32x32x16_bf16 v[80:95], v[140:143], v[112:115], 0
	v_fmamk_f32 v36, v36, 0x3e38aa3b, v163
	v_fmamk_f32 v52, v52, 0x3e38aa3b, v163
	v_exp_f32_e32 v36, v36
	v_exp_f32_e32 v52, v52
	ds_read_b128 v[140:143], v243 offset:13888
	s_waitcnt lgkmcnt(11)
	v_mfma_f32_32x32x16_bf16 v[64:79], v[144:147], v[116:119], v[64:79]
	v_cvt_pk_bf16_f32 v97, v34, v35
	v_cvt_pk_bf16_f32 v105, v50, v51
	v_fmamk_f32 v37, v37, 0x3e38aa3b, v163
	v_fmamk_f32 v53, v53, 0x3e38aa3b, v163
	v_exp_f32_e32 v37, v37
	ds_read_b128 v[144:147], v243 offset:9312
	s_waitcnt lgkmcnt(11)
	v_mfma_f32_32x32x16_bf16 v[80:95], v[148:151], v[116:119], v[80:95]
	v_exp_f32_e32 v53, v53
	v_fmamk_f32 v38, v38, 0x3e38aa3b, v163
	v_fmamk_f32 v54, v54, 0x3e38aa3b, v163
	v_exp_f32_e32 v38, v38
	v_exp_f32_e32 v54, v54
	ds_read_b128 v[148:151], v243 offset:13920
	s_waitcnt lgkmcnt(5)
	v_mfma_f32_32x32x16_bf16 v[64:79], v[136:139], v[120:123], v[64:79]
	v_cvt_pk_bf16_f32 v98, v36, v37
	v_cvt_pk_bf16_f32 v106, v52, v53
	v_fmamk_f32 v39, v39, 0x3e38aa3b, v163
	v_fmamk_f32 v55, v55, 0x3e38aa3b, v163
	v_exp_f32_e32 v39, v39
	s_waitcnt lgkmcnt(2)
	v_mfma_f32_32x32x16_bf16 v[80:95], v[140:143], v[120:123], v[80:95]
	v_exp_f32_e32 v55, v55
	v_fmamk_f32 v40, v40, 0x3e38aa3b, v163
	v_fmamk_f32 v56, v56, 0x3e38aa3b, v163
	v_exp_f32_e32 v40, v40
	s_waitcnt vmcnt(3)
	ds_write_b128 v218, v[152:155]
	s_waitcnt vmcnt(2)
	ds_write_b128 v224, v[156:159]
	s_waitcnt lgkmcnt(3)
	v_mfma_f32_32x32x16_bf16 v[64:79], v[144:147], v[124:127], v[64:79]
	v_exp_f32_e32 v56, v56
	v_cvt_pk_bf16_f32 v99, v38, v39
	v_cvt_pk_bf16_f32 v107, v54, v55
	v_fmamk_f32 v41, v41, 0x3e38aa3b, v163
	v_fmamk_f32 v57, v57, 0x3e38aa3b, v163
	v_exp_f32_e32 v41, v41
	s_waitcnt lgkmcnt(2)
	v_mfma_f32_32x32x16_bf16 v[80:95], v[148:151], v[124:127], v[80:95]
	v_exp_f32_e32 v57, v57
	v_fmamk_f32 v42, v42, 0x3e38aa3b, v163
	v_fmamk_f32 v58, v58, 0x3e38aa3b, v163
	v_exp_f32_e32 v42, v42
	v_mfma_f32_32x32x16_bf16 v[0:15], v[192:195], v[100:103], v[0:15]
	v_exp_f32_e32 v58, v58
	v_fmamk_f32 v43, v43, 0x3e38aa3b, v163
	v_fmamk_f32 v59, v59, 0x3e38aa3b, v163
	v_exp_f32_e32 v43, v43
	v_exp_f32_e32 v59, v59
	ds_read_b64_tr_b16 v[176:177], v223 offset:0
	ds_read_b64_tr_b16 v[178:179], v223 offset:1536
	v_mfma_f32_32x32x16_bf16 v[16:31], v[196:199], v[100:103], v[16:31]
	v_fmamk_f32 v44, v44, 0x3e38aa3b, v163
	v_fmamk_f32 v60, v60, 0x3e38aa3b, v163
	v_exp_f32_e32 v44, v44
	v_exp_f32_e32 v60, v60
	ds_read_b64_tr_b16 v[180:181], v223 offset:64
	ds_read_b64_tr_b16 v[182:183], v223 offset:1600
	v_mfma_f32_32x32x16_bf16 v[226:241], v[246:249], v[100:103], v[226:241]
	v_cvt_pk_bf16_f32 v100, v40, v41
	v_cvt_pk_bf16_f32 v101, v42, v43
	v_fmamk_f32 v45, v45, 0x3e38aa3b, v163
	v_fmamk_f32 v61, v61, 0x3e38aa3b, v163
	v_exp_f32_e32 v45, v45
	v_exp_f32_e32 v61, v61
	ds_read_b64_tr_b16 v[184:185], v223 offset:6144
	ds_read_b64_tr_b16 v[186:187], v223 offset:7680
	v_mfma_f32_32x32x16_bf16 v[0:15], v[200:203], v[108:111], v[0:15]
	v_fmamk_f32 v46, v46, 0x3e38aa3b, v163
	v_fmamk_f32 v62, v62, 0x3e38aa3b, v163
	v_exp_f32_e32 v46, v46
	v_exp_f32_e32 v62, v62
	ds_read_b64_tr_b16 v[188:189], v223 offset:6208
	ds_read_b64_tr_b16 v[190:191], v223 offset:7744
	v_mfma_f32_32x32x16_bf16 v[16:31], v[204:207], v[108:111], v[16:31]
	v_cvt_pk_bf16_f32 v102, v44, v45
	v_fmamk_f32 v47, v47, 0x3e38aa3b, v163
	v_fmamk_f32 v63, v63, 0x3e38aa3b, v163
	v_exp_f32_e32 v47, v47
	v_exp_f32_e32 v63, v63
	v_mfma_f32_32x32x16_bf16 v[226:241], v[246:249], v[108:111], v[226:241]
	v_cvt_pk_bf16_f32 v108, v56, v57
	v_cvt_pk_bf16_f32 v109, v58, v59
	v_cvt_pk_bf16_f32 v110, v60, v61
	v_cvt_pk_bf16_f32 v103, v46, v47
	v_cvt_pk_bf16_f32 v111, v62, v63
	s_cmp_lg_u32 s9, 0
	s_cbranch_scc0 .Lagqa_noresc_5
	s_nop 15
	v_pk_mul_f32 v[0:1], v[0:1], v[166:167] op_sel_hi:[1,0]
	v_pk_mul_f32 v[2:3], v[2:3], v[166:167] op_sel_hi:[1,0]
	v_pk_mul_f32 v[4:5], v[4:5], v[166:167] op_sel_hi:[1,0]
	v_pk_mul_f32 v[6:7], v[6:7], v[166:167] op_sel_hi:[1,0]
	v_pk_mul_f32 v[8:9], v[8:9], v[166:167] op_sel_hi:[1,0]
	v_pk_mul_f32 v[10:11], v[10:11], v[166:167] op_sel_hi:[1,0]
	v_pk_mul_f32 v[12:13], v[12:13], v[166:167] op_sel_hi:[1,0]
	v_pk_mul_f32 v[14:15], v[14:15], v[166:167] op_sel_hi:[1,0]
	v_pk_mul_f32 v[16:17], v[16:17], v[166:167] op_sel_hi:[1,0]
	v_pk_mul_f32 v[18:19], v[18:19], v[166:167] op_sel_hi:[1,0]
	v_pk_mul_f32 v[20:21], v[20:21], v[166:167] op_sel_hi:[1,0]
	v_pk_mul_f32 v[22:23], v[22:23], v[166:167] op_sel_hi:[1,0]
	v_pk_mul_f32 v[24:25], v[24:25], v[166:167] op_sel_hi:[1,0]
	v_pk_mul_f32 v[26:27], v[26:27], v[166:167] op_sel_hi:[1,0]
	v_pk_mul_f32 v[28:29], v[28:29], v[166:167] op_sel_hi:[1,0]
	v_pk_mul_f32 v[30:31], v[30:31], v[166:167] op_sel_hi:[1,0]
	v_mul_f32_e32 v226, v226, v166

.Lagqa_tail:
	ds_read_b128 v[136:139], v243 offset:0
	ds_read_b128 v[140:143], v243 offset:4608
	ds_read_b128 v[144:147], v243 offset:32
	ds_read_b128 v[148:151], v243 offset:4640
	v_mfma_f32_32x32x16_bf16 v[0:15], v[176:179], v[96:99], v[0:15]
	v_max3_f32 v168, v64, v65, v66
	v_max3_f32 v170, v80, v81, v82
	v_max3_f32 v168, v168, v67, v68
	v_max3_f32 v170, v170, v83, v84
	v_max3_f32 v168, v168, v69, v70
	v_max3_f32 v170, v170, v85, v86
	v_max3_f32 v168, v168, v71, v72
	s_mov_b32 s55, s52
	s_mov_b32 s52, s53
	s_mov_b32 s53, s54
	s_mov_b32 s54, s55
	s_mov_b32 s9, 0
	v_mfma_f32_32x32x16_bf16 v[16:31], v[180:183], v[96:99], v[16:31]
	v_max3_f32 v170, v170, v87, v88
	v_max3_f32 v168, v168, v73, v74
	v_max3_f32 v170, v170, v89, v90
	v_max3_f32 v168, v168, v75, v76
	v_max3_f32 v170, v170, v91, v92
	v_max3_f32 v168, v168, v77, v78
	v_max3_f32 v170, v170, v93, v94
	global_load_dwordx4 v[156:159], v225, s[4:5]
	s_add_u32 s4, s4, 0x2000
	s_addc_u32 s5, s5, 0
	v_add_u32_e32 v222, s53, v220
	v_add_u32_e32 v224, s54, v221
	v_mfma_f32_32x32x16_bf16 v[226:241], v[246:249], v[96:99], v[226:241]
	v_max_f32_e32 v168, v168, v79
	v_max_f32_e32 v170, v170, v95
	v_max_f32_e32 v168, v168, v170
	v_mov_b32_e32 v170, v168
	s_nop 1
	v_permlane32_swap_b32_e32 v168, v170
	v_max_f32_e32 v168, v168, v170
	v_mul_f32_e32 v168, 0x3e38aa3b, v168
	v_mfma_f32_32x32x16_bf16 v[0:15], v[184:187], v[104:107], v[0:15]
	v_cmp_gt_f32_e32 vcc, v168, v164
	s_cbranch_vccz .Lagqa_nors_6
	v_max_f32_e32 v170, v162, v168
	v_sub_f32_e32 v166, v162, v170
	v_exp_f32_e32 v166, v166
	v_mov_b32_e32 v162, v170
	v_add_f32_e32 v164, 0x41000000, v170
	v_xor_b32_e32 v163, 0x80000000, v170
	s_mov_b32 s9, 1
.Lagqa_nors_6:
	v_fmamk_f32 v64, v64, 0x3e38aa3b, v163
	v_fmamk_f32 v80, v80, 0x3e38aa3b, v163
	v_exp_f32_e32 v64, v64
	ds_read_b64_tr_b16 v[192:193], v223 offset:3072
	ds_read_b64_tr_b16 v[194:195], v223 offset:4608
	v_mfma_f32_32x32x16_bf16 v[16:31], v[188:191], v[104:107], v[16:31]
	v_exp_f32_e32 v80, v80
	v_fmamk_f32 v65, v65, 0x3e38aa3b, v163
	v_fmamk_f32 v81, v81, 0x3e38aa3b, v163
	v_exp_f32_e32 v65, v65
	v_exp_f32_e32 v81, v81
	ds_read_b64_tr_b16 v[196:197], v223 offset:3136
	ds_read_b64_tr_b16 v[198:199], v223 offset:4672
	v_mfma_f32_32x32x16_bf16 v[226:241], v[246:249], v[104:107], v[226:241]
	v_fmamk_f32 v66, v66, 0x3e38aa3b, v163
	v_fmamk_f32 v82, v82, 0x3e38aa3b, v163
	v_exp_f32_e32 v66, v66
	v_exp_f32_e32 v82, v82
	ds_read_b64_tr_b16 v[200:201], v223 offset:9216
	ds_read_b64_tr_b16 v[202:203], v223 offset:10752
	s_waitcnt lgkmcnt(9)
	v_mfma_f32_32x32x16_bf16 v[32:47], v[136:139], v[112:115], 0
	v_cvt_pk_bf16_f32 v96, v64, v65
	v_cvt_pk_bf16_f32 v104, v80, v81
	v_fmamk_f32 v67, v67, 0x3e38aa3b, v163
	v_fmamk_f32 v83, v83, 0x3e38aa3b, v163
	v_exp_f32_e32 v67, v67
	v_exp_f32_e32 v83, v83
	ds_read_b128 v[136:139], v243 offset:64
	ds_read_b64_tr_b16 v[204:205], v223 offset:9280
	ds_read_b64_tr_b16 v[206:207], v223 offset:10816
	s_waitcnt lgkmcnt(11)
	v_mfma_f32_32x32x16_bf16 v[48:63], v[140:143], v[112:115], 0
	v_fmamk_f32 v68, v68, 0x3e38aa3b, v163
	v_fmamk_f32 v84, v84, 0x3e38aa3b, v163
	v_exp_f32_e32 v68, v68
	v_exp_f32_e32 v84, v84
	ds_read_b128 v[140:143], v243 offset:4672
	s_waitcnt lgkmcnt(11)
	v_mfma_f32_32x32x16_bf16 v[32:47], v[144:147], v[116:119], v[32:47]
	v_cvt_pk_bf16_f32 v97, v66, v67
	v_cvt_pk_bf16_f32 v105, v82, v83
	v_fmamk_f32 v69, v69, 0x3e38aa3b, v163
	v_fmamk_f32 v85, v85, 0x3e38aa3b, v163
	v_exp_f32_e32 v69, v69
	ds_read_b128 v[144:147], v243 offset:96
	s_waitcnt lgkmcnt(11)
	v_mfma_f32_32x32x16_bf16 v[48:63], v[148:151], v[116:119], v[48:63]
	v_exp_f32_e32 v85, v85
	v_fmamk_f32 v70, v70, 0x3e38aa3b, v163
	v_fmamk_f32 v86, v86, 0x3e38aa3b, v163
	v_exp_f32_e32 v70, v70
	v_exp_f32_e32 v86, v86
	ds_read_b128 v[148:151], v243 offset:4704
	s_waitcnt lgkmcnt(5)
	v_mfma_f32_32x32x16_bf16 v[32:47], v[136:139], v[120:123], v[32:47]
	v_cvt_pk_bf16_f32 v98, v68, v69
	v_cvt_pk_bf16_f32 v106, v84, v85
	v_fmamk_f32 v71, v71, 0x3e38aa3b, v163
	v_fmamk_f32 v87, v87, 0x3e38aa3b, v163
	v_exp_f32_e32 v71, v71
	s_waitcnt lgkmcnt(2)
	v_mfma_f32_32x32x16_bf16 v[48:63], v[140:143], v[120:123], v[48:63]
	v_exp_f32_e32 v87, v87
	v_fmamk_f32 v72, v72, 0x3e38aa3b, v163
	v_fmamk_f32 v88, v88, 0x3e38aa3b, v163
	v_exp_f32_e32 v72, v72
	s_waitcnt vmcnt(2)
	ds_write_b128 v218, v[208:211] offset:9216
	s_waitcnt vmcnt(1)
	ds_write_b128 v224, v[212:215]
	s_waitcnt lgkmcnt(3)
	v_mfma_f32_32x32x16_bf16 v[32:47], v[144:147], v[124:127], v[32:47]
	v_exp_f32_e32 v88, v88
	v_cvt_pk_bf16_f32 v99, v70, v71
	v_cvt_pk_bf16_f32 v107, v86, v87
	v_fmamk_f32 v73, v73, 0x3e38aa3b, v163
	v_fmamk_f32 v89, v89, 0x3e38aa3b, v163
	v_exp_f32_e32 v73, v73
	s_waitcnt lgkmcnt(2)
	v_mfma_f32_32x32x16_bf16 v[48:63], v[148:151], v[124:127], v[48:63]
	v_exp_f32_e32 v89, v89
	v_fmamk_f32 v74, v74, 0x3e38aa3b, v163
	v_fmamk_f32 v90, v90, 0x3e38aa3b, v163
	v_exp_f32_e32 v74, v74
	v_mfma_f32_32x32x16_bf16 v[0:15], v[192:195], v[100:103], v[0:15]
	v_exp_f32_e32 v90, v90
	v_fmamk_f32 v75, v75, 0x3e38aa3b, v163
	v_fmamk_f32 v91, v91, 0x3e38aa3b, v163
	v_exp_f32_e32 v75, v75
	v_exp_f32_e32 v91, v91
	ds_read_b64_tr_b16 v[176:177], v222 offset:0
	ds_read_b64_tr_b16 v[178:179], v222 offset:1536
	v_mfma_f32_32x32x16_bf16 v[16:31], v[196:199], v[100:103], v[16:31]
	v_fmamk_f32 v76, v76, 0x3e38aa3b, v163
	v_fmamk_f32 v92, v92, 0x3e38aa3b, v163
	v_exp_f32_e32 v76, v76
	v_exp_f32_e32 v92, v92
	ds_read_b64_tr_b16 v[180:181], v222 offset:64
	ds_read_b64_tr_b16 v[182:183], v222 offset:1600
	v_mfma_f32_32x32x16_bf16 v[226:241], v[246:249], v[100:103], v[226:241]
	v_cvt_pk_bf16_f32 v100, v72, v73
	v_cvt_pk_bf16_f32 v101, v74, v75
	v_fmamk_f32 v77, v77, 0x3e38aa3b, v163
	v_fmamk_f32 v93, v93, 0x3e38aa3b, v163
	v_exp_f32_e32 v77, v77
	v_exp_f32_e32 v93, v93
	ds_read_b64_tr_b16 v[184:185], v222 offset:6144
	ds_read_b64_tr_b16 v[186:187], v222 offset:7680
	v_mfma_f32_32x32x16_bf16 v[0:15], v[200:203], v[108:111], v[0:15]
	v_fmamk_f32 v78, v78, 0x3e38aa3b, v163
	v_fmamk_f32 v94, v94, 0x3e38aa3b, v163
	v_exp_f32_e32 v78, v78
	v_exp_f32_e32 v94, v94
	ds_read_b64_tr_b16 v[188:189], v222 offset:6208
	ds_read_b64_tr_b16 v[190:191], v222 offset:7744
	v_mfma_f32_32x32x16_bf16 v[16:31], v[204:207], v[108:111], v[16:31]
	v_cvt_pk_bf16_f32 v102, v76, v77
	v_fmamk_f32 v79, v79, 0x3e38aa3b, v163
	v_fmamk_f32 v95, v95, 0x3e38aa3b, v163
	v_exp_f32_e32 v79, v79
	v_exp_f32_e32 v95, v95
	v_mfma_f32_32x32x16_bf16 v[226:241], v[246:249], v[108:111], v[226:241]
	v_cvt_pk_bf16_f32 v108, v88, v89
	v_cvt_pk_bf16_f32 v109, v90, v91
	v_cvt_pk_bf16_f32 v110, v92, v93
	v_cvt_pk_bf16_f32 v103, v78, v79
	v_cvt_pk_bf16_f32 v111, v94, v95
	s_cmp_lg_u32 s9, 0
	s_cbranch_scc0 .Lagqa_noresc_7
	s_nop 15
	v_pk_mul_f32 v[0:1], v[0:1], v[166:167] op_sel_hi:[1,0]
	v_pk_mul_f32 v[2:3], v[2:3], v[166:167] op_sel_hi:[1,0]
	v_pk_mul_f32 v[4:5], v[4:5], v[166:167] op_sel_hi:[1,0]
	v_pk_mul_f32 v[6:7], v[6:7], v[166:167] op_sel_hi:[1,0]
	v_pk_mul_f32 v[8:9], v[8:9], v[166:167] op_sel_hi:[1,0]
	v_pk_mul_f32 v[10:11], v[10:11], v[166:167] op_sel_hi:[1,0]
	v_pk_mul_f32 v[12:13], v[12:13], v[166:167] op_sel_hi:[1,0]
	v_pk_mul_f32 v[14:15], v[14:15], v[166:167] op_sel_hi:[1,0]
	v_pk_mul_f32 v[16:17], v[16:17], v[166:167] op_sel_hi:[1,0]
	v_pk_mul_f32 v[18:19], v[18:19], v[166:167] op_sel_hi:[1,0]
	v_pk_mul_f32 v[20:21], v[20:21], v[166:167] op_sel_hi:[1,0]
	v_pk_mul_f32 v[22:23], v[22:23], v[166:167] op_sel_hi:[1,0]
	v_pk_mul_f32 v[24:25], v[24:25], v[166:167] op_sel_hi:[1,0]
	v_pk_mul_f32 v[26:27], v[26:27], v[166:167] op_sel_hi:[1,0]
	v_pk_mul_f32 v[28:29], v[28:29], v[166:167] op_sel_hi:[1,0]
	v_pk_mul_f32 v[30:31], v[30:31], v[166:167] op_sel_hi:[1,0]
	v_mul_f32_e32 v226, v226, v166
.Lagqa_noresc_7:
	s_waitcnt lgkmcnt(0)
	s_barrier
	ds_read_b128 v[136:139], v243 offset:9216
	ds_read_b128 v[140:143], v243 offset:13824
	ds_read_b128 v[144:147], v243 offset:9248
	ds_read_b128 v[148:151], v243 offset:13856
	v_mfma_f32_32x32x16_bf16 v[0:15], v[176:179], v[96:99], v[0:15]
	v_max3_f32 v168, v32, v33, v34
	v_max3_f32 v170, v48, v49, v50
	v_max3_f32 v168, v168, v35, v36
	v_max3_f32 v170, v170, v51, v52
	v_max3_f32 v168, v168, v37, v38
	v_max3_f32 v170, v170, v53, v54
	v_max3_f32 v168, v168, v39, v40
	s_mov_b32 s55, s52
	s_mov_b32 s52, s53
	s_mov_b32 s53, s54
	s_mov_b32 s54, s55
	s_mov_b32 s9, 0
	v_mfma_f32_32x32x16_bf16 v[16:31], v[180:183], v[96:99], v[16:31]
	v_max3_f32 v170, v170, v55, v56
	v_max3_f32 v168, v168, v41, v42
	v_max3_f32 v170, v170, v57, v58
	v_max3_f32 v168, v168, v43, v44
	v_max3_f32 v170, v170, v59, v60
	v_max3_f32 v168, v168, v45, v46
	v_max3_f32 v170, v170, v61, v62
	v_add_u32_e32 v223, s53, v220
	v_add_u32_e32 v224, s54, v221
	v_mfma_f32_32x32x16_bf16 v[226:241], v[246:249], v[96:99], v[226:241]
	v_max_f32_e32 v168, v168, v47
	v_max_f32_e32 v170, v170, v63
	v_max_f32_e32 v168, v168, v170
	v_mov_b32_e32 v170, v168
	s_nop 1
	v_permlane32_swap_b32_e32 v168, v170
	v_max_f32_e32 v168, v168, v170
	v_mul_f32_e32 v168, 0x3e38aa3b, v168
	v_mfma_f32_32x32x16_bf16 v[0:15], v[184:187], v[104:107], v[0:15]
	v_cmp_gt_f32_e32 vcc, v168, v164
	s_cbranch_vccz .Lagqa_nors_8
	v_max_f32_e32 v170, v162, v168
	v_sub_f32_e32 v166, v162, v170
	v_exp_f32_e32 v166, v166
	v_mov_b32_e32 v162, v170
	v_add_f32_e32 v164, 0x41000000, v170
	v_xor_b32_e32 v163, 0x80000000, v170
	s_mov_b32 s9, 1
.Lagqa_nors_8:
	v_fmamk_f32 v32, v32, 0x3e38aa3b, v163
	v_fmamk_f32 v48, v48, 0x3e38aa3b, v163
	v_exp_f32_e32 v32, v32
	ds_read_b64_tr_b16 v[192:193], v222 offset:3072
	ds_read_b64_tr_b16 v[194:195], v222 offset:4608
	v_mfma_f32_32x32x16_bf16 v[16:31], v[188:191], v[104:107], v[16:31]
	v_exp_f32_e32 v48, v48
	v_fmamk_f32 v33, v33, 0x3e38aa3b, v163
	v_fmamk_f32 v49, v49, 0x3e38aa3b, v163
	v_exp_f32_e32 v33, v33
	v_exp_f32_e32 v49, v49
	ds_read_b64_tr_b16 v[196:197], v222 offset:3136
	ds_read_b64_tr_b16 v[198:199], v222 offset:4672
	v_mfma_f32_32x32x16_bf16 v[226:241], v[246:249], v[104:107], v[226:241]
	v_fmamk_f32 v34, v34, 0x3e38aa3b, v163
	v_fmamk_f32 v50, v50, 0x3e38aa3b, v163
	v_exp_f32_e32 v34, v34
	v_exp_f32_e32 v50, v50
	ds_read_b64_tr_b16 v[200:201], v222 offset:9216
	ds_read_b64_tr_b16 v[202:203], v222 offset:10752
	s_waitcnt lgkmcnt(9)
	v_mfma_f32_32x32x16_bf16 v[64:79], v[136:139], v[112:115], 0
	v_cvt_pk_bf16_f32 v96, v32, v33
	v_cvt_pk_bf16_f32 v104, v48, v49
	v_fmamk_f32 v35, v35, 0x3e38aa3b, v163
	v_fmamk_f32 v51, v51, 0x3e38aa3b, v163
	v_exp_f32_e32 v35, v35
	v_exp_f32_e32 v51, v51
	ds_read_b128 v[136:139], v243 offset:9280
	ds_read_b64_tr_b16 v[204:205], v222 offset:9280
	ds_read_b64_tr_b16 v[206:207], v222 offset:10816
	s_waitcnt lgkmcnt(11)
	v_mfma_f32_32x32x16_bf16 v[80:95], v[140:143], v[112:115], 0
	v_fmamk_f32 v36, v36, 0x3e38aa3b, v163
	v_fmamk_f32 v52, v52, 0x3e38aa3b, v163
	v_exp_f32_e32 v36, v36
	v_exp_f32_e32 v52, v52
	ds_read_b128 v[140:143], v243 offset:13888
	s_waitcnt lgkmcnt(11)
	v_mfma_f32_32x32x16_bf16 v[64:79], v[144:147], v[116:119], v[64:79]
	v_cvt_pk_bf16_f32 v97, v34, v35
	v_cvt_pk_bf16_f32 v105, v50, v51
	v_fmamk_f32 v37, v37, 0x3e38aa3b, v163
	v_fmamk_f32 v53, v53, 0x3e38aa3b, v163
	v_exp_f32_e32 v37, v37
	ds_read_b128 v[144:147], v243 offset:9312
	s_waitcnt lgkmcnt(11)
	v_mfma_f32_32x32x16_bf16 v[80:95], v[148:151], v[116:119], v[80:95]
	v_exp_f32_e32 v53, v53
	v_fmamk_f32 v38, v38, 0x3e38aa3b, v163
	v_fmamk_f32 v54, v54, 0x3e38aa3b, v163
	v_exp_f32_e32 v38, v38
	v_exp_f32_e32 v54, v54
	ds_read_b128 v[148:151], v243 offset:13920
	s_waitcnt lgkmcnt(5)
	v_mfma_f32_32x32x16_bf16 v[64:79], v[136:139], v[120:123], v[64:79]
	v_cvt_pk_bf16_f32 v98, v36, v37
	v_cvt_pk_bf16_f32 v106, v52, v53
	v_fmamk_f32 v39, v39, 0x3e38aa3b, v163
	v_fmamk_f32 v55, v55, 0x3e38aa3b, v163
	v_exp_f32_e32 v39, v39
	s_waitcnt lgkmcnt(2)
	v_mfma_f32_32x32x16_bf16 v[80:95], v[140:143], v[120:123], v[80:95]
	v_exp_f32_e32 v55, v55
	v_fmamk_f32 v40, v40, 0x3e38aa3b, v163
	v_fmamk_f32 v56, v56, 0x3e38aa3b, v163
	v_exp_f32_e32 v40, v40
	s_waitcnt vmcnt(0)
	ds_write_b128 v224, v[156:159]
	s_waitcnt lgkmcnt(2)
	v_mfma_f32_32x32x16_bf16 v[64:79], v[144:147], v[124:127], v[64:79]
	v_exp_f32_e32 v56, v56
	v_cvt_pk_bf16_f32 v99, v38, v39
	v_cvt_pk_bf16_f32 v107, v54, v55
	v_fmamk_f32 v41, v41, 0x3e38aa3b, v163
	v_fmamk_f32 v57, v57, 0x3e38aa3b, v163
	v_exp_f32_e32 v41, v41
	s_waitcnt lgkmcnt(1)
	v_mfma_f32_32x32x16_bf16 v[80:95], v[148:151], v[124:127], v[80:95]
	v_exp_f32_e32 v57, v57
	v_fmamk_f32 v42, v42, 0x3e38aa3b, v163
	v_fmamk_f32 v58, v58, 0x3e38aa3b, v163
	v_exp_f32_e32 v42, v42
	v_mfma_f32_32x32x16_bf16 v[0:15], v[192:195], v[100:103], v[0:15]
	v_exp_f32_e32 v58, v58
	v_fmamk_f32 v43, v43, 0x3e38aa3b, v163
	v_fmamk_f32 v59, v59, 0x3e38aa3b, v163
	v_exp_f32_e32 v43, v43
	v_exp_f32_e32 v59, v59
	ds_read_b64_tr_b16 v[176:177], v223 offset:0
	ds_read_b64_tr_b16 v[178:179], v223 offset:1536
	v_mfma_f32_32x32x16_bf16 v[16:31], v[196:199], v[100:103], v[16:31]
	v_fmamk_f32 v44, v44, 0x3e38aa3b, v163
	v_fmamk_f32 v60, v60, 0x3e38aa3b, v163
	v_exp_f32_e32 v44, v44
	v_exp_f32_e32 v60, v60
	ds_read_b64_tr_b16 v[180:181], v223 offset:64
	ds_read_b64_tr_b16 v[182:183], v223 offset:1600
	v_mfma_f32_32x32x16_bf16 v[226:241], v[246:249], v[100:103], v[226:241]
	v_cvt_pk_bf16_f32 v100, v40, v41
	v_cvt_pk_bf16_f32 v101, v42, v43
	v_fmamk_f32 v45, v45, 0x3e38aa3b, v163
	v_fmamk_f32 v61, v61, 0x3e38aa3b, v163
	v_exp_f32_e32 v45, v45
	v_exp_f32_e32 v61, v61
	ds_read_b64_tr_b16 v[184:185], v223 offset:6144
	ds_read_b64_tr_b16 v[186:187], v223 offset:7680
	v_mfma_f32_32x32x16_bf16 v[0:15], v[200:203], v[108:111], v[0:15]
	v_fmamk_f32 v46, v46, 0x3e38aa3b, v163
	v_fmamk_f32 v62, v62, 0x3e38aa3b, v163
	v_exp_f32_e32 v46, v46
	v_exp_f32_e32 v62, v62
	ds_read_b64_tr_b16 v[188:189], v223 offset:6208
	ds_read_b64_tr_b16 v[190:191], v223 offset:7744
	v_mfma_f32_32x32x16_bf16 v[16:31], v[204:207], v[108:111], v[16:31]
	v_cvt_pk_bf16_f32 v102, v44, v45
	v_fmamk_f32 v47, v47, 0x3e38aa3b, v163
	v_fmamk_f32 v63, v63, 0x3e38aa3b, v163
	v_exp_f32_e32 v47, v47
	v_exp_f32_e32 v63, v63
	v_mfma_f32_32x32x16_bf16 v[226:241], v[246:249], v[108:111], v[226:241]
	v_cvt_pk_bf16_f32 v108, v56, v57
	v_cvt_pk_bf16_f32 v109, v58, v59
	v_cvt_pk_bf16_f32 v110, v60, v61
	v_cvt_pk_bf16_f32 v103, v46, v47
	v_cvt_pk_bf16_f32 v111, v62, v63
	s_cmp_lg_u32 s9, 0
	s_cbranch_scc0 .Lagqa_noresc_9
	s_nop 15
	v_pk_mul_f32 v[0:1], v[0:1], v[166:167] op_sel_hi:[1,0]
	v_pk_mul_f32 v[2:3], v[2:3], v[166:167] op_sel_hi:[1,0]
	v_pk_mul_f32 v[4:5], v[4:5], v[166:167] op_sel_hi:[1,0]
	v_pk_mul_f32 v[6:7], v[6:7], v[166:167] op_sel_hi:[1,0]
	v_pk_mul_f32 v[8:9], v[8:9], v[166:167] op_sel_hi:[1,0]
	v_pk_mul_f32 v[10:11], v[10:11], v[166:167] op_sel_hi:[1,0]
	v_pk_mul_f32 v[12:13], v[12:13], v[166:167] op_sel_hi:[1,0]
	v_pk_mul_f32 v[14:15], v[14:15], v[166:167] op_sel_hi:[1,0]
	v_pk_mul_f32 v[16:17], v[16:17], v[166:167] op_sel_hi:[1,0]
	v_pk_mul_f32 v[18:19], v[18:19], v[166:167] op_sel_hi:[1,0]
	v_pk_mul_f32 v[20:21], v[20:21], v[166:167] op_sel_hi:[1,0]
	v_pk_mul_f32 v[22:23], v[22:23], v[166:167] op_sel_hi:[1,0]
	v_pk_mul_f32 v[24:25], v[24:25], v[166:167] op_sel_hi:[1,0]
	v_pk_mul_f32 v[26:27], v[26:27], v[166:167] op_sel_hi:[1,0]
	v_pk_mul_f32 v[28:29], v[28:29], v[166:167] op_sel_hi:[1,0]
	v_pk_mul_f32 v[30:31], v[30:31], v[166:167] op_sel_hi:[1,0]
	v_mul_f32_e32 v226, v226, v166
.Lagqa_noresc_9:
	s_waitcnt lgkmcnt(0)
	s_barrier
	ds_read_b64_tr_b16 v[192:193], v223 offset:3072
	ds_read_b64_tr_b16 v[194:195], v223 offset:4608
	ds_read_b64_tr_b16 v[196:197], v223 offset:3136
	ds_read_b64_tr_b16 v[198:199], v223 offset:4672
	v_mfma_f32_32x32x16_bf16 v[0:15], v[176:179], v[96:99], v[0:15]
	v_max3_f32 v168, v64, v65, v66
	v_max3_f32 v170, v80, v81, v82
	v_max3_f32 v168, v168, v67, v68
	v_max3_f32 v170, v170, v83, v84
	v_max3_f32 v168, v168, v69, v70
	v_max3_f32 v170, v170, v85, v86
	v_max3_f32 v168, v168, v71, v72
	v_max3_f32 v170, v170, v87, v88
	v_max3_f32 v168, v168, v73, v74
	v_max3_f32 v170, v170, v89, v90
	v_max3_f32 v168, v168, v75, v76
	v_max3_f32 v170, v170, v91, v92
	s_mov_b32 s55, s52
	s_mov_b32 s52, s53
	s_mov_b32 s53, s54
	s_mov_b32 s54, s55
	s_mov_b32 s9, 0
	ds_read_b64_tr_b16 v[200:201], v223 offset:9216
	ds_read_b64_tr_b16 v[202:203], v223 offset:10752
	ds_read_b64_tr_b16 v[204:205], v223 offset:9280
	ds_read_b64_tr_b16 v[206:207], v223 offset:10816
	v_mfma_f32_32x32x16_bf16 v[16:31], v[180:183], v[96:99], v[16:31]
	v_max3_f32 v168, v168, v77, v78
	v_max3_f32 v170, v170, v93, v94
	v_max_f32_e32 v168, v168, v79
	v_max_f32_e32 v170, v170, v95
	v_max_f32_e32 v168, v168, v170
	v_mov_b32_e32 v170, v168
	s_nop 1
	v_permlane32_swap_b32_e32 v168, v170
	v_max_f32_e32 v168, v168, v170
	v_mul_f32_e32 v168, 0x3e38aa3b, v168
	v_cmp_gt_f32_e32 vcc, v168, v164
	s_cbranch_vccz .Lagqa_nors_10
	v_max_f32_e32 v170, v162, v168
	v_sub_f32_e32 v166, v162, v170
	v_exp_f32_e32 v166, v166
	v_mov_b32_e32 v162, v170
	v_add_f32_e32 v164, 0x41000000, v170
	v_xor_b32_e32 v163, 0x80000000, v170
	s_mov_b32 s9, 1
.Lagqa_nors_10:
	v_add_u32_e32 v222, s53, v220
	v_mfma_f32_32x32x16_bf16 v[226:241], v[246:249], v[96:99], v[226:241]
	v_fmamk_f32 v64, v64, 0x3e38aa3b, v163
	v_fmamk_f32 v80, v80, 0x3e38aa3b, v163
	v_exp_f32_e32 v64, v64
	v_exp_f32_e32 v80, v80
	v_fmamk_f32 v65, v65, 0x3e38aa3b, v163
	v_fmamk_f32 v81, v81, 0x3e38aa3b, v163
	v_exp_f32_e32 v65, v65
	v_exp_f32_e32 v81, v81
	v_mfma_f32_32x32x16_bf16 v[0:15], v[184:187], v[104:107], v[0:15]
	v_fmamk_f32 v66, v66, 0x3e38aa3b, v163
	v_fmamk_f32 v82, v82, 0x3e38aa3b, v163
	v_exp_f32_e32 v66, v66
	v_exp_f32_e32 v82, v82
	v_cvt_pk_bf16_f32 v96, v64, v65
	v_fmamk_f32 v67, v67, 0x3e38aa3b, v163
	v_fmamk_f32 v83, v83, 0x3e38aa3b, v163
	v_exp_f32_e32 v67, v67
	v_mfma_f32_32x32x16_bf16 v[16:31], v[188:191], v[104:107], v[16:31]
	v_exp_f32_e32 v83, v83
	v_fmamk_f32 v68, v68, 0x3e38aa3b, v163
	v_fmamk_f32 v84, v84, 0x3e38aa3b, v163
	v_exp_f32_e32 v68, v68
	v_exp_f32_e32 v84, v84
	v_cvt_pk_bf16_f32 v97, v66, v67
	v_fmamk_f32 v69, v69, 0x3e38aa3b, v163
	v_fmamk_f32 v85, v85, 0x3e38aa3b, v163
	v_mfma_f32_32x32x16_bf16 v[226:241], v[246:249], v[104:107], v[226:241]
	v_cvt_pk_bf16_f32 v104, v80, v81
	v_cvt_pk_bf16_f32 v105, v82, v83
	v_exp_f32_e32 v69, v69
	v_exp_f32_e32 v85, v85
	v_fmamk_f32 v70, v70, 0x3e38aa3b, v163
	v_fmamk_f32 v86, v86, 0x3e38aa3b, v163
	v_exp_f32_e32 v70, v70
	v_exp_f32_e32 v86, v86
	v_cvt_pk_bf16_f32 v98, v68, v69
	s_waitcnt lgkmcnt(6)
	v_mfma_f32_32x32x16_bf16 v[0:15], v[192:195], v[100:103], v[0:15]
	v_cvt_pk_bf16_f32 v106, v84, v85
	v_fmamk_f32 v71, v71, 0x3e38aa3b, v163
	v_fmamk_f32 v87, v87, 0x3e38aa3b, v163
	v_exp_f32_e32 v71, v71
	v_exp_f32_e32 v87, v87
	v_fmamk_f32 v72, v72, 0x3e38aa3b, v163
	v_fmamk_f32 v88, v88, 0x3e38aa3b, v163
	v_exp_f32_e32 v72, v72
	ds_read_b64_tr_b16 v[176:177], v222 offset:0
	ds_read_b64_tr_b16 v[178:179], v222 offset:1536
	s_waitcnt lgkmcnt(6)
	v_mfma_f32_32x32x16_bf16 v[16:31], v[196:199], v[100:103], v[16:31]
	v_exp_f32_e32 v88, v88
	v_cvt_pk_bf16_f32 v99, v70, v71
	v_cvt_pk_bf16_f32 v107, v86, v87
	v_fmamk_f32 v73, v73, 0x3e38aa3b, v163
	v_fmamk_f32 v89, v89, 0x3e38aa3b, v163
	v_exp_f32_e32 v73, v73
	v_exp_f32_e32 v89, v89
	v_fmamk_f32 v74, v74, 0x3e38aa3b, v163
	ds_read_b64_tr_b16 v[180:181], v222 offset:64
	ds_read_b64_tr_b16 v[182:183], v222 offset:1600
	v_mfma_f32_32x32x16_bf16 v[226:241], v[246:249], v[100:103], v[226:241]
	v_fmamk_f32 v90, v90, 0x3e38aa3b, v163
	v_exp_f32_e32 v74, v74
	v_exp_f32_e32 v90, v90
	v_cvt_pk_bf16_f32 v100, v72, v73
	v_fmamk_f32 v75, v75, 0x3e38aa3b, v163
	v_fmamk_f32 v91, v91, 0x3e38aa3b, v163
	v_exp_f32_e32 v75, v75
	v_exp_f32_e32 v91, v91
	ds_read_b64_tr_b16 v[184:185], v222 offset:6144
	ds_read_b64_tr_b16 v[186:187], v222 offset:7680
	s_waitcnt lgkmcnt(8)
	v_mfma_f32_32x32x16_bf16 v[0:15], v[200:203], v[108:111], v[0:15]
	v_fmamk_f32 v76, v76, 0x3e38aa3b, v163
	v_fmamk_f32 v92, v92, 0x3e38aa3b, v163
	v_exp_f32_e32 v76, v76
	v_exp_f32_e32 v92, v92
	v_cvt_pk_bf16_f32 v101, v74, v75
	v_fmamk_f32 v77, v77, 0x3e38aa3b, v163
	v_fmamk_f32 v93, v93, 0x3e38aa3b, v163
	v_exp_f32_e32 v77, v77
	ds_read_b64_tr_b16 v[188:189], v222 offset:6208
	ds_read_b64_tr_b16 v[190:191], v222 offset:7744
	s_waitcnt lgkmcnt(8)
	v_mfma_f32_32x32x16_bf16 v[16:31], v[204:207], v[108:111], v[16:31]
	v_exp_f32_e32 v93, v93
	v_fmamk_f32 v78, v78, 0x3e38aa3b, v163
	v_fmamk_f32 v94, v94, 0x3e38aa3b, v163
	v_exp_f32_e32 v78, v78
	v_exp_f32_e32 v94, v94
	v_cvt_pk_bf16_f32 v102, v76, v77
	v_fmamk_f32 v79, v79, 0x3e38aa3b, v163
	v_fmamk_f32 v95, v95, 0x3e38aa3b, v163
	v_mfma_f32_32x32x16_bf16 v[226:241], v[246:249], v[108:111], v[226:241]
	v_cvt_pk_bf16_f32 v108, v88, v89
	v_cvt_pk_bf16_f32 v109, v90, v91
	v_cvt_pk_bf16_f32 v110, v92, v93
	v_exp_f32_e32 v79, v79
	v_exp_f32_e32 v95, v95
	v_cvt_pk_bf16_f32 v103, v78, v79
	v_cvt_pk_bf16_f32 v111, v94, v95
	s_cmp_lg_u32 s9, 0
	s_cbranch_scc0 .Lagqa_noresc_11
	s_nop 15
	v_pk_mul_f32 v[0:1], v[0:1], v[166:167] op_sel_hi:[1,0]
	v_pk_mul_f32 v[2:3], v[2:3], v[166:167] op_sel_hi:[1,0]
	v_pk_mul_f32 v[4:5], v[4:5], v[166:167] op_sel_hi:[1,0]
	v_pk_mul_f32 v[6:7], v[6:7], v[166:167] op_sel_hi:[1,0]
	v_pk_mul_f32 v[8:9], v[8:9], v[166:167] op_sel_hi:[1,0]
	v_pk_mul_f32 v[10:11], v[10:11], v[166:167] op_sel_hi:[1,0]
	v_pk_mul_f32 v[12:13], v[12:13], v[166:167] op_sel_hi:[1,0]
	v_pk_mul_f32 v[14:15], v[14:15], v[166:167] op_sel_hi:[1,0]
	v_pk_mul_f32 v[16:17], v[16:17], v[166:167] op_sel_hi:[1,0]
	v_pk_mul_f32 v[18:19], v[18:19], v[166:167] op_sel_hi:[1,0]
	v_pk_mul_f32 v[20:21], v[20:21], v[166:167] op_sel_hi:[1,0]
	v_pk_mul_f32 v[22:23], v[22:23], v[166:167] op_sel_hi:[1,0]
	v_pk_mul_f32 v[24:25], v[24:25], v[166:167] op_sel_hi:[1,0]
	v_pk_mul_f32 v[26:27], v[26:27], v[166:167] op_sel_hi:[1,0]
	v_pk_mul_f32 v[28:29], v[28:29], v[166:167] op_sel_hi:[1,0]
	v_pk_mul_f32 v[30:31], v[30:31], v[166:167] op_sel_hi:[1,0]
	v_mul_f32_e32 v226, v226, v166
